# latent GLA chunk-start states pre-scanned once per (b,h,d) slice at m2 phase start into dead hbuf scratch, published with release+counter; latent gla_m2 jobs load their start state after an acquire in
# speedup vs baseline: 1.0261x; 1.0172x over previous
.LBB0_591:
	s_or_b64 exec, exec, s[0:1]
	v_readlane_b32 s0, v253, 14
	v_readlane_b32 s1, v253, 15
	s_mov_b64 s[64:65], s[84:85]
	s_mov_b32 s66, s86
	s_and_b64 vcc, exec, s[0:1]
	s_waitcnt lgkmcnt(0)
	s_barrier
	s_cbranch_vccnz .LBB0_723
	s_mov_b32 s63, s66
	s_cmpk_gt_u32 s63, 0xff
	s_cbranch_scc1 .Lps_done0
.Lps_loop0:
	s_and_b32 s0, s63, 7
	s_lshr_b32 s1, s63, 3
	s_lshr_b32 s2, s1, 4
	s_bfe_u32 s3, s1, 0x10003
	s_and_b32 s4, s1, 7
	s_lshl_b32 s5, s2, 5
	s_add_i32 s5, s5, 64
	s_mov_b32 s6, 0x80000
	s_movk_i32 s8, 0x1000
	s_cmp_eq_u32 s3, 0
	s_cselect_b32 s10, 0, 31
	s_cselect_b32 s6, s6, 0xfff80000
	s_cselect_b32 s7, 0, -1
	s_cselect_b32 s8, s8, 0xfffff000
	s_cselect_b32 s9, 0, -1
	s_add_i32 s5, s5, s10
	s_lshl_b32 s11, s5, 3
	s_or_b32 s11, s11, s0
	s_lshl_b32 s11, s11, 1
	s_or_b32 s11, s11, s3
	s_lshl_b32 s16, s4, 12
	s_mov_b32 s12, s11
	s_mov_b32 s13, 0
	s_lshl_b64 s[12:13], s[12:13], 15
	s_add_u32 s12, s12, s42
	s_addc_u32 s13, s13, s43
	s_add_u32 s12, s12, s16
	s_addc_u32 s13, s13, 0
	s_mov_b32 s14, s11
	s_mov_b32 s15, 0
	s_lshl_b64 s[14:15], s[14:15], 8
	s_add_u32 s14, s14, s44
	s_addc_u32 s15, s15, s45
	v_readlane_b32 s52, v254, 16
	v_readlane_b32 s53, v254, 17
	s_sub_i32 s54, s11, 0x400
	s_mov_b32 s55, 0
	s_lshl_b64 s[54:55], s[54:55], 15
	s_add_u32 s52, s52, s54
	s_addc_u32 s53, s53, s55
	s_add_u32 s52, s52, s16
	s_addc_u32 s53, s53, 0
	v_readlane_b32 s56, v254, 36
	v_readlane_b32 s57, v254, 37
	s_lshl_b32 s58, s2, 1
	s_lshl_b32 s58, s58, 1
	s_or_b32 s58, s58, s3
	s_lshl_b32 s58, s58, 3
	s_or_b32 s58, s58, s0
	s_mov_b32 s59, 0
	s_lshl_b64 s[58:59], s[58:59], 15
	s_add_u32 s56, s56, s58
	s_addc_u32 s57, s57, s59
	s_lshl_b32 s58, s4, 6
	s_add_u32 s56, s56, s58
	s_addc_u32 s57, s57, 0
	v_lshlrev_b32_e32 v0, 3, v180
	v_mov_b32_e32 v1, 0
	v_and_b32_e32 v10, 31, v180
	v_lshlrev_b32_e32 v12, 10, v10
	v_lshlrev_b32_e32 v10, 3, v10
	v_mov_b32_e32 v11, 0
	v_lshrrev_b32_e32 v13, 5, v180
	v_lshl_add_u32 v12, v13, 2, v12
	global_load_dword v8, v12, s[56:57]
	global_load_dword v9, v12, s[56:57] offset:512
	v_lshl_add_u64 v[2:3], s[12:13], 0, v[0:1]
	v_lshl_add_u64 v[4:5], s[14:15], 0, v[10:11]
	v_lshl_add_u64 v[6:7], s[52:53], 0, v[0:1]
	global_load_dwordx2 v[16:17], v[2:3], off
	v_lshl_add_u64 v[2:3], v[2:3], 0, s[6:7]
	global_load_dwordx2 v[48:49], v[4:5], off
	v_lshl_add_u64 v[4:5], v[4:5], 0, s[8:9]
	global_load_dwordx2 v[18:19], v[2:3], off
	v_lshl_add_u64 v[2:3], v[2:3], 0, s[6:7]
	global_load_dwordx2 v[50:51], v[4:5], off
	v_lshl_add_u64 v[4:5], v[4:5], 0, s[8:9]
	global_load_dwordx2 v[20:21], v[2:3], off
	v_lshl_add_u64 v[2:3], v[2:3], 0, s[6:7]
	global_load_dwordx2 v[52:53], v[4:5], off
	v_lshl_add_u64 v[4:5], v[4:5], 0, s[8:9]
	global_load_dwordx2 v[22:23], v[2:3], off
	v_lshl_add_u64 v[2:3], v[2:3], 0, s[6:7]
	global_load_dwordx2 v[54:55], v[4:5], off
	v_lshl_add_u64 v[4:5], v[4:5], 0, s[8:9]
	global_load_dwordx2 v[24:25], v[2:3], off
	v_lshl_add_u64 v[2:3], v[2:3], 0, s[6:7]
	global_load_dwordx2 v[56:57], v[4:5], off
	v_lshl_add_u64 v[4:5], v[4:5], 0, s[8:9]
	global_load_dwordx2 v[26:27], v[2:3], off
	v_lshl_add_u64 v[2:3], v[2:3], 0, s[6:7]
	global_load_dwordx2 v[58:59], v[4:5], off
	v_lshl_add_u64 v[4:5], v[4:5], 0, s[8:9]
	global_load_dwordx2 v[28:29], v[2:3], off
	v_lshl_add_u64 v[2:3], v[2:3], 0, s[6:7]
	global_load_dwordx2 v[60:61], v[4:5], off
	v_lshl_add_u64 v[4:5], v[4:5], 0, s[8:9]
	global_load_dwordx2 v[30:31], v[2:3], off
	v_lshl_add_u64 v[2:3], v[2:3], 0, s[6:7]
	global_load_dwordx2 v[62:63], v[4:5], off
	v_lshl_add_u64 v[4:5], v[4:5], 0, s[8:9]
	global_load_dwordx2 v[32:33], v[2:3], off
	v_lshl_add_u64 v[2:3], v[2:3], 0, s[6:7]
	global_load_dwordx2 v[64:65], v[4:5], off
	v_lshl_add_u64 v[4:5], v[4:5], 0, s[8:9]
	global_load_dwordx2 v[34:35], v[2:3], off
	v_lshl_add_u64 v[2:3], v[2:3], 0, s[6:7]
	global_load_dwordx2 v[66:67], v[4:5], off
	v_lshl_add_u64 v[4:5], v[4:5], 0, s[8:9]
	global_load_dwordx2 v[36:37], v[2:3], off
	v_lshl_add_u64 v[2:3], v[2:3], 0, s[6:7]
	global_load_dwordx2 v[68:69], v[4:5], off
	v_lshl_add_u64 v[4:5], v[4:5], 0, s[8:9]
	global_load_dwordx2 v[38:39], v[2:3], off
	v_lshl_add_u64 v[2:3], v[2:3], 0, s[6:7]
	global_load_dwordx2 v[70:71], v[4:5], off
	v_lshl_add_u64 v[4:5], v[4:5], 0, s[8:9]
	global_load_dwordx2 v[40:41], v[2:3], off
	v_lshl_add_u64 v[2:3], v[2:3], 0, s[6:7]
	global_load_dwordx2 v[72:73], v[4:5], off
	v_lshl_add_u64 v[4:5], v[4:5], 0, s[8:9]
	global_load_dwordx2 v[42:43], v[2:3], off
	v_lshl_add_u64 v[2:3], v[2:3], 0, s[6:7]
	global_load_dwordx2 v[74:75], v[4:5], off
	v_lshl_add_u64 v[4:5], v[4:5], 0, s[8:9]
	global_load_dwordx2 v[44:45], v[2:3], off
	v_lshl_add_u64 v[2:3], v[2:3], 0, s[6:7]
	global_load_dwordx2 v[76:77], v[4:5], off
	v_lshl_add_u64 v[4:5], v[4:5], 0, s[8:9]
	global_load_dwordx2 v[46:47], v[2:3], off
	v_lshl_add_u64 v[2:3], v[2:3], 0, s[6:7]
	global_load_dwordx2 v[78:79], v[4:5], off
	v_lshl_add_u64 v[4:5], v[4:5], 0, s[8:9]
	s_waitcnt vmcnt(30)
	global_store_dwordx2 v[6:7], v[8:9], off
	v_lshl_add_u64 v[6:7], v[6:7], 0, s[6:7]
	v_pk_fma_f32 v[8:9], v[8:9], v[48:49], v[16:17]
	s_waitcnt vmcnt(29)
	global_store_dwordx2 v[6:7], v[8:9], off
	v_lshl_add_u64 v[6:7], v[6:7], 0, s[6:7]
	v_pk_fma_f32 v[8:9], v[8:9], v[50:51], v[18:19]
	s_waitcnt vmcnt(28)
	global_store_dwordx2 v[6:7], v[8:9], off
	v_lshl_add_u64 v[6:7], v[6:7], 0, s[6:7]
	v_pk_fma_f32 v[8:9], v[8:9], v[52:53], v[20:21]
	s_waitcnt vmcnt(27)
	global_store_dwordx2 v[6:7], v[8:9], off
	v_lshl_add_u64 v[6:7], v[6:7], 0, s[6:7]
	v_pk_fma_f32 v[8:9], v[8:9], v[54:55], v[22:23]
	s_waitcnt vmcnt(26)
	global_store_dwordx2 v[6:7], v[8:9], off
	v_lshl_add_u64 v[6:7], v[6:7], 0, s[6:7]
	v_pk_fma_f32 v[8:9], v[8:9], v[56:57], v[24:25]
	s_waitcnt vmcnt(25)
	global_store_dwordx2 v[6:7], v[8:9], off
	v_lshl_add_u64 v[6:7], v[6:7], 0, s[6:7]
	v_pk_fma_f32 v[8:9], v[8:9], v[58:59], v[26:27]
	s_waitcnt vmcnt(24)
	global_store_dwordx2 v[6:7], v[8:9], off
	v_lshl_add_u64 v[6:7], v[6:7], 0, s[6:7]
	v_pk_fma_f32 v[8:9], v[8:9], v[60:61], v[28:29]
	s_waitcnt vmcnt(23)
	global_store_dwordx2 v[6:7], v[8:9], off
	v_lshl_add_u64 v[6:7], v[6:7], 0, s[6:7]
	v_pk_fma_f32 v[8:9], v[8:9], v[62:63], v[30:31]
	s_waitcnt vmcnt(22)
	global_store_dwordx2 v[6:7], v[8:9], off
	v_lshl_add_u64 v[6:7], v[6:7], 0, s[6:7]
	v_pk_fma_f32 v[8:9], v[8:9], v[64:65], v[32:33]
	s_waitcnt vmcnt(21)
	global_store_dwordx2 v[6:7], v[8:9], off
	v_lshl_add_u64 v[6:7], v[6:7], 0, s[6:7]
	v_pk_fma_f32 v[8:9], v[8:9], v[66:67], v[34:35]
	s_waitcnt vmcnt(20)
	global_store_dwordx2 v[6:7], v[8:9], off
	v_lshl_add_u64 v[6:7], v[6:7], 0, s[6:7]
	v_pk_fma_f32 v[8:9], v[8:9], v[68:69], v[36:37]
	s_waitcnt vmcnt(19)
	global_store_dwordx2 v[6:7], v[8:9], off
	v_lshl_add_u64 v[6:7], v[6:7], 0, s[6:7]
	v_pk_fma_f32 v[8:9], v[8:9], v[70:71], v[38:39]
	s_waitcnt vmcnt(18)
	global_store_dwordx2 v[6:7], v[8:9], off
	v_lshl_add_u64 v[6:7], v[6:7], 0, s[6:7]
	v_pk_fma_f32 v[8:9], v[8:9], v[72:73], v[40:41]
	s_waitcnt vmcnt(17)
	global_store_dwordx2 v[6:7], v[8:9], off
	v_lshl_add_u64 v[6:7], v[6:7], 0, s[6:7]
	v_pk_fma_f32 v[8:9], v[8:9], v[74:75], v[42:43]
	s_waitcnt vmcnt(16)
	global_store_dwordx2 v[6:7], v[8:9], off
	v_lshl_add_u64 v[6:7], v[6:7], 0, s[6:7]
	v_pk_fma_f32 v[8:9], v[8:9], v[76:77], v[44:45]
	s_waitcnt vmcnt(15)
	global_store_dwordx2 v[6:7], v[8:9], off
	v_lshl_add_u64 v[6:7], v[6:7], 0, s[6:7]
	v_pk_fma_f32 v[8:9], v[8:9], v[78:79], v[46:47]
	global_load_dwordx2 v[16:17], v[2:3], off
	v_lshl_add_u64 v[2:3], v[2:3], 0, s[6:7]
	global_load_dwordx2 v[48:49], v[4:5], off
	v_lshl_add_u64 v[4:5], v[4:5], 0, s[8:9]
	global_load_dwordx2 v[18:19], v[2:3], off
	v_lshl_add_u64 v[2:3], v[2:3], 0, s[6:7]
	global_load_dwordx2 v[50:51], v[4:5], off
	v_lshl_add_u64 v[4:5], v[4:5], 0, s[8:9]
	global_load_dwordx2 v[20:21], v[2:3], off
	v_lshl_add_u64 v[2:3], v[2:3], 0, s[6:7]
	global_load_dwordx2 v[52:53], v[4:5], off
	v_lshl_add_u64 v[4:5], v[4:5], 0, s[8:9]
	global_load_dwordx2 v[22:23], v[2:3], off
	v_lshl_add_u64 v[2:3], v[2:3], 0, s[6:7]
	global_load_dwordx2 v[54:55], v[4:5], off
	v_lshl_add_u64 v[4:5], v[4:5], 0, s[8:9]
	global_load_dwordx2 v[24:25], v[2:3], off
	v_lshl_add_u64 v[2:3], v[2:3], 0, s[6:7]
	global_load_dwordx2 v[56:57], v[4:5], off
	v_lshl_add_u64 v[4:5], v[4:5], 0, s[8:9]
	global_load_dwordx2 v[26:27], v[2:3], off
	v_lshl_add_u64 v[2:3], v[2:3], 0, s[6:7]
	global_load_dwordx2 v[58:59], v[4:5], off
	v_lshl_add_u64 v[4:5], v[4:5], 0, s[8:9]
	global_load_dwordx2 v[28:29], v[2:3], off
	v_lshl_add_u64 v[2:3], v[2:3], 0, s[6:7]
	global_load_dwordx2 v[60:61], v[4:5], off
	v_lshl_add_u64 v[4:5], v[4:5], 0, s[8:9]
	global_load_dwordx2 v[30:31], v[2:3], off
	v_lshl_add_u64 v[2:3], v[2:3], 0, s[6:7]
	global_load_dwordx2 v[62:63], v[4:5], off
	v_lshl_add_u64 v[4:5], v[4:5], 0, s[8:9]
	global_load_dwordx2 v[32:33], v[2:3], off
	v_lshl_add_u64 v[2:3], v[2:3], 0, s[6:7]
	global_load_dwordx2 v[64:65], v[4:5], off
	v_lshl_add_u64 v[4:5], v[4:5], 0, s[8:9]
	global_load_dwordx2 v[34:35], v[2:3], off
	v_lshl_add_u64 v[2:3], v[2:3], 0, s[6:7]
	global_load_dwordx2 v[66:67], v[4:5], off
	v_lshl_add_u64 v[4:5], v[4:5], 0, s[8:9]
	global_load_dwordx2 v[36:37], v[2:3], off
	v_lshl_add_u64 v[2:3], v[2:3], 0, s[6:7]
	global_load_dwordx2 v[68:69], v[4:5], off
	v_lshl_add_u64 v[4:5], v[4:5], 0, s[8:9]
	global_load_dwordx2 v[38:39], v[2:3], off
	v_lshl_add_u64 v[2:3], v[2:3], 0, s[6:7]
	global_load_dwordx2 v[70:71], v[4:5], off
	v_lshl_add_u64 v[4:5], v[4:5], 0, s[8:9]
	global_load_dwordx2 v[40:41], v[2:3], off
	v_lshl_add_u64 v[2:3], v[2:3], 0, s[6:7]
	global_load_dwordx2 v[72:73], v[4:5], off
	v_lshl_add_u64 v[4:5], v[4:5], 0, s[8:9]
	global_load_dwordx2 v[42:43], v[2:3], off
	v_lshl_add_u64 v[2:3], v[2:3], 0, s[6:7]
	global_load_dwordx2 v[74:75], v[4:5], off
	v_lshl_add_u64 v[4:5], v[4:5], 0, s[8:9]
	global_load_dwordx2 v[44:45], v[2:3], off
	v_lshl_add_u64 v[2:3], v[2:3], 0, s[6:7]
	global_load_dwordx2 v[76:77], v[4:5], off
	v_lshl_add_u64 v[4:5], v[4:5], 0, s[8:9]
	global_load_dwordx2 v[46:47], v[2:3], off
	v_lshl_add_u64 v[2:3], v[2:3], 0, s[6:7]
	global_load_dwordx2 v[78:79], v[4:5], off
	v_lshl_add_u64 v[4:5], v[4:5], 0, s[8:9]
	s_waitcnt vmcnt(30)
	global_store_dwordx2 v[6:7], v[8:9], off
	v_lshl_add_u64 v[6:7], v[6:7], 0, s[6:7]
	v_pk_fma_f32 v[8:9], v[8:9], v[48:49], v[16:17]
	s_waitcnt vmcnt(29)
	global_store_dwordx2 v[6:7], v[8:9], off
	v_lshl_add_u64 v[6:7], v[6:7], 0, s[6:7]
	v_pk_fma_f32 v[8:9], v[8:9], v[50:51], v[18:19]
	s_waitcnt vmcnt(28)
	global_store_dwordx2 v[6:7], v[8:9], off
	v_lshl_add_u64 v[6:7], v[6:7], 0, s[6:7]
	v_pk_fma_f32 v[8:9], v[8:9], v[52:53], v[20:21]
	s_waitcnt vmcnt(27)
	global_store_dwordx2 v[6:7], v[8:9], off
	v_lshl_add_u64 v[6:7], v[6:7], 0, s[6:7]
	v_pk_fma_f32 v[8:9], v[8:9], v[54:55], v[22:23]
	s_waitcnt vmcnt(26)
	global_store_dwordx2 v[6:7], v[8:9], off
	v_lshl_add_u64 v[6:7], v[6:7], 0, s[6:7]
	v_pk_fma_f32 v[8:9], v[8:9], v[56:57], v[24:25]
	s_waitcnt vmcnt(25)
	global_store_dwordx2 v[6:7], v[8:9], off
	v_lshl_add_u64 v[6:7], v[6:7], 0, s[6:7]
	v_pk_fma_f32 v[8:9], v[8:9], v[58:59], v[26:27]
	s_waitcnt vmcnt(24)
	global_store_dwordx2 v[6:7], v[8:9], off
	v_lshl_add_u64 v[6:7], v[6:7], 0, s[6:7]
	v_pk_fma_f32 v[8:9], v[8:9], v[60:61], v[28:29]
	s_waitcnt vmcnt(23)
	global_store_dwordx2 v[6:7], v[8:9], off
	v_lshl_add_u64 v[6:7], v[6:7], 0, s[6:7]
	v_pk_fma_f32 v[8:9], v[8:9], v[62:63], v[30:31]
	s_waitcnt vmcnt(22)
	global_store_dwordx2 v[6:7], v[8:9], off
	v_lshl_add_u64 v[6:7], v[6:7], 0, s[6:7]
	v_pk_fma_f32 v[8:9], v[8:9], v[64:65], v[32:33]
	s_waitcnt vmcnt(21)
	global_store_dwordx2 v[6:7], v[8:9], off
	v_lshl_add_u64 v[6:7], v[6:7], 0, s[6:7]
	v_pk_fma_f32 v[8:9], v[8:9], v[66:67], v[34:35]
	s_waitcnt vmcnt(20)
	global_store_dwordx2 v[6:7], v[8:9], off
	v_lshl_add_u64 v[6:7], v[6:7], 0, s[6:7]
	v_pk_fma_f32 v[8:9], v[8:9], v[68:69], v[36:37]
	s_waitcnt vmcnt(19)
	global_store_dwordx2 v[6:7], v[8:9], off
	v_lshl_add_u64 v[6:7], v[6:7], 0, s[6:7]
	v_pk_fma_f32 v[8:9], v[8:9], v[70:71], v[38:39]
	s_waitcnt vmcnt(18)
	global_store_dwordx2 v[6:7], v[8:9], off
	v_lshl_add_u64 v[6:7], v[6:7], 0, s[6:7]
	v_pk_fma_f32 v[8:9], v[8:9], v[72:73], v[40:41]
	s_waitcnt vmcnt(17)
	global_store_dwordx2 v[6:7], v[8:9], off
	v_lshl_add_u64 v[6:7], v[6:7], 0, s[6:7]
	v_pk_fma_f32 v[8:9], v[8:9], v[74:75], v[42:43]
	s_waitcnt vmcnt(16)
	global_store_dwordx2 v[6:7], v[8:9], off
	v_lshl_add_u64 v[6:7], v[6:7], 0, s[6:7]
	v_pk_fma_f32 v[8:9], v[8:9], v[76:77], v[44:45]
	s_waitcnt vmcnt(15)
	global_store_dwordx2 v[6:7], v[8:9], off
	v_lshl_add_u64 v[6:7], v[6:7], 0, s[6:7]
	v_pk_fma_f32 v[8:9], v[8:9], v[78:79], v[46:47]
	s_add_i32 s63, s63, s64
	s_cmpk_lt_u32 s63, 0x100
	s_cbranch_scc1 .Lps_loop0
.Lps_done0:
	s_waitcnt vmcnt(0)
	s_barrier
	v_cmp_eq_u32_e64 s[10:11], 0, v180
	s_and_saveexec_b64 s[12:13], s[10:11]
	s_cbranch_execz .Lps_arrived0
	buffer_wbl2 sc1
	s_waitcnt vmcnt(0)
	v_readlane_b32 s14, v254, 2
	v_readlane_b32 s15, v254, 3
	v_mov_b32_e32 v0, 0
	v_mov_b32_e32 v1, 1
	s_nop 4
	global_atomic_add v0, v1, s[14:15] offset:16
.Lps_arrived0:
	s_or_b64 exec, exec, s[12:13]
	v_readlane_b32 s0, v254, 60
	v_readlane_b32 s10, v253, 6
	v_readlane_b32 s9, v253, 5
	v_readlane_b32 s11, v253, 7
	s_add_u32 s67, s10, 0x8040000
	s_addc_u32 s0, s11, 0
	s_mov_b32 s9, 0
	s_movk_i32 s92, 0x1000
	s_movk_i32 s93, 0x80
	v_mov_b32_e32 v177, 0
	s_mov_b32 s11, 0x42b504f3
	v_mov_b32_e32 v182, 0xf149f2ca
	s_mov_b32 s10, 0x3e0293ee
	s_movk_i32 s33, 0xfefe
	s_movk_i32 s84, 0x5040
	s_movk_i32 s85, 0x110
	s_add_i32 s86, 0, 0x11800
	s_movk_i32 s87, 0x90
	s_add_i32 s88, 0, 0x13c00
	s_add_i32 s89, 0, 0x16000
	s_add_i32 s52, 0, 0x18400
	s_add_i32 s53, 0, 0x1a800
	v_mbcnt_hi_u32_b32 v183, -1, v181
	v_mov_b32_e32 v184, 0x358637bd
	v_mov_b32_e32 v185, 0x80
	s_mov_b32 s54, s66
	v_readlane_b32 s1, v254, 61
	v_readlane_b32 s2, v254, 62
	v_readlane_b32 s3, v254, 63
	v_readlane_b32 s4, v253, 0
	v_readlane_b32 s5, v253, 1
	v_readlane_b32 s6, v253, 2
	v_readlane_b32 s7, v253, 3
	v_readlane_b32 s8, v253, 4
	v_readlane_b32 s12, v253, 8
	v_readlane_b32 s13, v253, 9
	v_readlane_b32 s14, v253, 10
	v_readlane_b32 s15, v253, 11
	v_writelane_b32 v253, s0, 19
	s_branch .LBB0_594

.LBB0_642:
	v_cmp_eq_u32_e64 s[0:1], 0, v180
	s_and_saveexec_b64 s[2:3], s[0:1]
	s_cbranch_execz .Lpw_done0
	v_readlane_b32 s4, v254, 2
	v_readlane_b32 s5, v254, 3
	v_mov_b32_e32 v0, 0
	s_mov_b32 s12, 0
	s_min_u32 s14, s64, 0x100
	s_nop 4
.Lpw_spin0:
	global_load_dword v1, v0, s[4:5] offset:16 sc1
	s_waitcnt vmcnt(0)
	v_readfirstlane_b32 s13, v1
	s_cmp_ge_u32 s13, s14
	s_cbranch_scc1 .Lpw_ok0
	s_add_u32 s12, s12, 1
	s_cmp_gt_u32 s12, 0x8000
	s_cbranch_scc1 .Lpw_ok0
	s_sleep 1
	s_branch .Lpw_spin0
.Lpw_ok0:
	buffer_inv sc1
	s_waitcnt vmcnt(0)
.Lpw_done0:
	s_or_b64 exec, exec, s[2:3]
	s_barrier
	s_and_b32 s55, s54, 7
	v_readlane_b32 s68, v254, 28
	s_lshl_b32 s0, s55, 6
	s_lshl_b32 s1, s55, 7
	s_lshl_b32 s2, s55, 15
	v_readlane_b32 s76, v254, 36
	v_readlane_b32 s77, v254, 37
	s_add_u32 s56, s76, s2
	v_readlane_b32 s69, v254, 29
	v_readlane_b32 s70, v254, 30
	v_readlane_b32 s71, v254, 31
	v_readlane_b32 s72, v254, 32
	v_readlane_b32 s73, v254, 33
	v_readlane_b32 s74, v254, 34
	v_readlane_b32 s75, v254, 35
	v_readlane_b32 s78, v254, 38
	v_readlane_b32 s79, v254, 39
	v_readlane_b32 s80, v254, 40
	v_readlane_b32 s81, v254, 41
	v_readlane_b32 s82, v254, 42
	v_readlane_b32 s83, v254, 43
	s_addc_u32 s57, s77, 0
	s_add_u32 s58, s67, s2
	v_readlane_b32 s2, v253, 19
	v_readlane_b32 s68, v254, 12
	s_addc_u32 s59, s2, 0
	s_lshl_b32 s2, s55, 8
	v_readlane_b32 s76, v254, 20
	v_readlane_b32 s77, v254, 21
	s_add_u32 s4, s76, s2
	s_addc_u32 s5, s77, 0
	s_mov_b32 s60, 0
	s_lshl_b32 s6, s0, 1
	s_lshl_b32 s8, s1, 1
	v_readlane_b32 s69, v254, 13
	v_readlane_b32 s70, v254, 14
	v_readlane_b32 s71, v254, 15
	v_readlane_b32 s72, v254, 16
	v_readlane_b32 s73, v254, 17
	v_readlane_b32 s74, v254, 18
	v_readlane_b32 s75, v254, 19
	v_readlane_b32 s78, v254, 22
	v_readlane_b32 s79, v254, 23
	v_readlane_b32 s80, v254, 24
	v_readlane_b32 s81, v254, 25
	v_readlane_b32 s82, v254, 26
	v_readlane_b32 s83, v254, 27
	s_branch .LBB0_644

.LBB0_644:
	s_lshl_b32 s0, s60, 8
	s_add_i32 s12, s0, s54
	s_mul_i32 s0, s12, 0x8200
	v_mov_b32_e32 v171, v180
	s_mul_hi_i32 s1, s12, 0x8200
	s_add_u32 s0, s46, s0
	s_movk_i32 s2, 0x820
	s_addc_u32 s1, s47, s1
	v_lshlrev_b32_e32 v120, 2, v171
	v_lshlrev_b32_e32 v186, 4, v171
	v_ashrrev_i32_e32 v121, 31, v120
	global_load_dwordx4 v[188:191], v186, s[0:1]
	v_add_u32_e32 v172, 0x200, v171
	v_add_u32_e32 v187, 0x2000, v186
	v_lshlrev_b32_e32 v126, 2, v172
	global_load_dwordx4 v[192:195], v187, s[0:1]
	v_add_u32_e32 v173, 0x400, v171
	v_add_u32_e32 v187, 0x4000, v186
	v_lshlrev_b32_e32 v124, 2, v173
	global_load_dwordx4 v[196:199], v187, s[0:1]
	v_add_u32_e32 v174, 0x600, v171
	v_add_u32_e32 v187, 0x6000, v186
	v_lshlrev_b32_e32 v122, 2, v174
	global_load_dwordx4 v[200:203], v187, s[0:1]
	v_cmp_gt_i32_e32 vcc, 32, v171
	v_add_u32_e32 v187, 0x8000, v186
	s_nop 1
	v_cndmask_b32_e32 v187, 0, v187, vcc
	global_load_dwordx4 v[204:207], v187, s[0:1]
	s_ashr_i32 s61, s12, 3
	s_lshl_b32 s0, s61, 6
	s_cmp_lt_i32 s61, 64
	s_cselect_b64 s[20:21], -1, 0
	s_add_i32 s1, s0, 0xfffff000
	s_lshr_b32 s1, s1, 11
	s_ashr_i32 s2, s12, 5
	s_cmp_gt_i32 s61, 63
	v_readlane_b32 s68, v254, 12
	s_cselect_b64 s[24:25], -1, 0
	v_ashrrev_i32_e32 v170, 3, v171
	v_readlane_b32 s74, v254, 18
	v_readlane_b32 s75, v254, 19
	s_and_b64 vcc, s[24:25], exec
	v_add_u32_e32 v116, s0, v170
	v_mov_b64_e32 v[0:1], s[74:75]
	s_cselect_b32 s13, s1, s2
	v_and_b32_e32 v11, 7, v171
	v_mad_i64_i32 v[118:119], s[0:1], v116, s84, v[0:1]
	s_mov_b32 s7, s9
	v_lshl_add_u64 v[0:1], v[118:119], 0, s[6:7]
	v_lshlrev_b32_e32 v176, 4, v11
	v_lshl_add_u64 v[0:1], v[0:1], 0, v[176:177]
	v_add_co_u32_e64 v4, s[0:1], s92, v0
	s_nop 1
	v_addc_co_u32_e64 v5, s[0:1], 0, v1, s[0:1]
	global_load_dwordx4 v[208:211], v[4:5], off
	global_load_dwordx4 v[212:215], v[4:5], off offset:1024
	s_waitcnt vmcnt(2)
	ds_write_b128 v186, v[188:191]
	ds_write_b128 v186, v[192:195] offset:8192
	ds_write_b128 v186, v[196:199] offset:16384
	ds_write_b128 v186, v[200:203] offset:24576
	v_cmp_gt_i32_e64 s[98:99], 32, v171
	s_and_saveexec_b64 s[62:63], s[98:99]
	ds_write_b128 v186, v[204:207] offset:32768
	s_mov_b64 exec, s[62:63]
	s_waitcnt lgkmcnt(0)
	s_barrier
	v_lshlrev_b32_e32 v8, 5, v11
	v_add_u32_e32 v10, 0, v8
	s_movk_i32 s0, 0x104
	v_mad_u64_u32 v[12:13], s[0:1], v170, s0, v[10:11]
	ds_read2_b32 v[14:15], v12 offset1:1
	v_add_u32_e32 v13, 0x607c, v10
	s_mov_b64 s[0:1], 0x1800
	v_mul_u32_u24_e32 v11, 0x900, v11
	s_lshl_b32 s14, s13, 2
	s_mov_b32 s15, s9
	s_mov_b32 s3, s9
	v_readlane_b32 s69, v254, 13
	v_readlane_b32 s70, v254, 14
	v_readlane_b32 s71, v254, 15
	v_readlane_b32 s72, v254, 16
	v_readlane_b32 s73, v254, 17
	v_readlane_b32 s76, v254, 20
	v_readlane_b32 s77, v254, 21
	v_readlane_b32 s78, v254, 22
	v_readlane_b32 s79, v254, 23
	v_readlane_b32 s80, v254, 24
	v_readlane_b32 s81, v254, 25
	v_readlane_b32 s82, v254, 26
	v_readlane_b32 s83, v254, 27
	s_waitcnt vmcnt(1)
	v_lshlrev_b32_e32 v6, 16, v208
	v_and_b32_e32 v20, 0xffff0000, v208
	v_lshlrev_b32_e32 v32, 16, v209
	v_and_b32_e32 v33, 0xffff0000, v209
	v_lshlrev_b32_e32 v40, 16, v210
	v_and_b32_e32 v41, 0xffff0000, v210
	v_lshlrev_b32_e32 v49, 16, v211
	v_and_b32_e32 v16, 0xffff0000, v211
	v_mul_f32_e32 v17, 0x3e000000, v6
	v_mul_f32_e32 v49, 0x3e000000, v49
	s_waitcnt vmcnt(0)
	v_lshlrev_b32_e32 v22, 16, v212
	v_and_b32_e32 v34, 0xffff0000, v212
	v_add_u32_e32 v0, 0x4100, v12
	v_lshlrev_b32_e32 v35, 16, v213
	v_and_b32_e32 v42, 0xffff0000, v213
	v_lshlrev_b32_e32 v37, 16, v214
	v_and_b32_e32 v50, 0xffff0000, v214
	v_lshlrev_b32_e32 v24, 16, v215
	v_and_b32_e32 v9, 0xffff0000, v215
	ds_read2_b32 v[28:29], v0 offset1:1
	ds_read_b128 v[4:7], v10 offset:8320
	ds_read_b128 v[0:3], v10 offset:8336
	ds_read2_b32 v[30:31], v13 offset1:1
	s_waitcnt lgkmcnt(4)
	v_mul_f32_e32 v13, 0x3fb8aa3b, v14
	v_exp_f32_e32 v13, v13
	s_nop 0
	v_mul_f32_e32 v23, v17, v13
	s_waitcnt lgkmcnt(3)
	v_mul_f32_e32 v13, 0x3fb8aa3b, v28
	v_exp_f32_e32 v13, v13
	s_nop 0
	v_mul_f32_e32 v21, v17, v13
	s_waitcnt lgkmcnt(2)
	v_sub_f32_e32 v13, v14, v4
	v_sub_f32_e32 v4, v4, v14
	v_mul_f32_e32 v4, 0x3fb8aa3b, v4
	v_exp_f32_e32 v4, v4
	v_mul_f32_e32 v13, 0x3fb8aa3b, v13
	v_exp_f32_e32 v13, v13
	v_mul_f32_e32 v14, 0x3fb8aa3b, v15
	v_mul_f32_e32 v18, v4, v22
	s_waitcnt lgkmcnt(0)
	v_sub_f32_e32 v4, v28, v30
	v_mul_f32_e32 v4, 0x3fb8aa3b, v4
	v_exp_f32_e32 v4, v4
	v_mul_f32_e32 v19, v17, v13
	v_exp_f32_e32 v14, v14
	v_mul_f32_e32 v17, v17, v4
	v_sub_f32_e32 v4, v30, v28
	v_mul_f32_e32 v4, 0x3fb8aa3b, v4
	v_exp_f32_e32 v4, v4
	s_nop 0
	v_mul_f32_e32 v13, v4, v22
	v_mul_f32_e32 v4, 0x3e000000, v20
	v_mul_f32_e32 v28, v4, v14
	v_mul_f32_e32 v14, 0x3fb8aa3b, v29
	v_exp_f32_e32 v14, v14
	s_nop 0
	v_mul_f32_e32 v27, v4, v14
	v_sub_f32_e32 v14, v15, v5
	v_sub_f32_e32 v5, v5, v15
	v_mul_f32_e32 v5, 0x3fb8aa3b, v5
	v_exp_f32_e32 v5, v5
	v_mul_f32_e32 v14, 0x3fb8aa3b, v14
	v_exp_f32_e32 v14, v14
	v_mul_f32_e32 v25, v5, v34
	v_sub_f32_e32 v5, v29, v31
	v_mul_f32_e32 v5, 0x3fb8aa3b, v5
	v_exp_f32_e32 v5, v5
	v_mul_f32_e32 v26, v4, v14
	ds_read2_b32 v[14:15], v12 offset0:2 offset1:3
	v_mul_f32_e32 v22, v4, v5
	v_sub_f32_e32 v4, v31, v29
	v_mul_f32_e32 v4, 0x3fb8aa3b, v4
	v_exp_f32_e32 v4, v4
	v_add_u32_e32 v29, 0x6084, v10
	ds_read2_b32 v[38:39], v29 offset1:1
	v_mul_f32_e32 v20, v4, v34
	v_add_u32_e32 v4, 0x4108, v12
	ds_read2_b32 v[4:5], v4 offset1:1
	s_waitcnt lgkmcnt(2)
	v_mul_f32_e32 v29, 0x3fb8aa3b, v14
	v_exp_f32_e32 v29, v29
	v_mul_f32_e32 v34, 0x3e000000, v32
	v_mul_f32_e32 v32, v34, v29
	s_waitcnt lgkmcnt(0)
	v_mul_f32_e32 v29, 0x3fb8aa3b, v4
	v_exp_f32_e32 v29, v29
	s_nop 0
	v_mul_f32_e32 v31, v34, v29
	v_sub_f32_e32 v29, v14, v6
	v_sub_f32_e32 v6, v6, v14
	v_mul_f32_e32 v29, 0x3fb8aa3b, v29
	v_mul_f32_e32 v6, 0x3fb8aa3b, v6
	v_exp_f32_e32 v29, v29
	v_exp_f32_e32 v6, v6
	v_mul_f32_e32 v30, v34, v29
	v_mul_f32_e32 v29, v6, v35
	v_sub_f32_e32 v6, v4, v38
	v_sub_f32_e32 v4, v38, v4
	v_mul_f32_e32 v6, 0x3fb8aa3b, v6
	v_mul_f32_e32 v4, 0x3fb8aa3b, v4
	v_exp_f32_e32 v6, v6
	v_exp_f32_e32 v4, v4
	v_mul_f32_e32 v38, 0x3e000000, v40
	v_mul_f32_e32 v14, v34, v6
	v_mul_f32_e32 v6, v4, v35
	v_mul_f32_e32 v4, 0x3e000000, v33
	v_mul_f32_e32 v33, 0x3fb8aa3b, v15
	v_exp_f32_e32 v33, v33
	s_nop 0
	v_mul_f32_e32 v36, v4, v33
	v_mul_f32_e32 v33, 0x3fb8aa3b, v5
	v_exp_f32_e32 v33, v33
	s_nop 0
	v_mul_f32_e32 v35, v4, v33
	v_sub_f32_e32 v33, v15, v7
	v_sub_f32_e32 v7, v7, v15
	v_mul_f32_e32 v33, 0x3fb8aa3b, v33
	v_mul_f32_e32 v7, 0x3fb8aa3b, v7
	v_exp_f32_e32 v33, v33
	v_exp_f32_e32 v7, v7
	v_mul_f32_e32 v34, v4, v33
	v_mul_f32_e32 v33, v7, v42
	v_sub_f32_e32 v7, v5, v39
	v_mul_f32_e32 v7, 0x3fb8aa3b, v7
	v_exp_f32_e32 v7, v7
	s_nop 0
	v_mul_f32_e32 v15, v4, v7
	v_sub_f32_e32 v4, v39, v5
	v_mul_f32_e32 v4, 0x3fb8aa3b, v4
	v_exp_f32_e32 v4, v4
	v_add_u32_e32 v39, 0x4110, v12
	ds_read2_b32 v[52:53], v39 offset1:1
	v_add_u32_e32 v39, 0x608c, v10
	v_mul_f32_e32 v7, v4, v42
	ds_read2_b32 v[4:5], v12 offset0:4 offset1:5
	ds_read2_b32 v[54:55], v39 offset1:1
	v_add_u32_e32 v10, 0x6094, v10
	s_waitcnt lgkmcnt(1)
	v_mul_f32_e32 v39, 0x3fb8aa3b, v4
	v_exp_f32_e32 v39, v39
	s_nop 0
	v_mul_f32_e32 v44, v38, v39
	v_mul_f32_e32 v39, 0x3fb8aa3b, v52
	v_exp_f32_e32 v39, v39
	s_nop 0
	v_mul_f32_e32 v42, v38, v39
	v_sub_f32_e32 v39, v4, v0
	v_sub_f32_e32 v0, v0, v4
	v_mul_f32_e32 v39, 0x3fb8aa3b, v39
	v_mul_f32_e32 v0, 0x3fb8aa3b, v0
	v_exp_f32_e32 v39, v39
	v_exp_f32_e32 v0, v0
	v_mul_f32_e32 v4, 0x3fb8aa3b, v5
	v_exp_f32_e32 v4, v4
	v_mul_f32_e32 v40, v38, v39
	v_mul_f32_e32 v39, v0, v37
	s_waitcnt lgkmcnt(0)
	v_sub_f32_e32 v0, v52, v54
	v_mul_f32_e32 v0, 0x3fb8aa3b, v0
	v_exp_f32_e32 v0, v0
	s_nop 0
	v_mul_f32_e32 v38, v38, v0
	v_sub_f32_e32 v0, v54, v52
	v_mul_f32_e32 v0, 0x3fb8aa3b, v0
	v_exp_f32_e32 v0, v0
	s_nop 0
	v_mul_f32_e32 v37, v0, v37
	v_mul_f32_e32 v0, 0x3e000000, v41
	v_mul_f32_e32 v48, v0, v4
	v_mul_f32_e32 v4, 0x3fb8aa3b, v53
	v_exp_f32_e32 v4, v4
	s_nop 0
	v_mul_f32_e32 v47, v0, v4
	v_sub_f32_e32 v4, v5, v1
	v_sub_f32_e32 v1, v1, v5
	v_mul_f32_e32 v1, 0x3fb8aa3b, v1
	v_exp_f32_e32 v1, v1
	v_mul_f32_e32 v4, 0x3fb8aa3b, v4
	v_exp_f32_e32 v4, v4
	v_mul_f32_e32 v45, v1, v50
	v_sub_f32_e32 v1, v53, v55
	v_mul_f32_e32 v1, 0x3fb8aa3b, v1
	v_exp_f32_e32 v1, v1
	v_mul_f32_e32 v46, v0, v4
	v_add_u32_e32 v4, 0x4118, v12
	ds_read2_b32 v[4:5], v4 offset1:1
	v_mul_f32_e32 v43, v0, v1
	v_sub_f32_e32 v0, v55, v53
	v_mul_f32_e32 v0, 0x3fb8aa3b, v0
	v_exp_f32_e32 v0, v0
	s_nop 0
	v_mul_f32_e32 v41, v0, v50
	ds_read2_b32 v[0:1], v12 offset0:6 offset1:7
	ds_read2_b32 v[50:51], v10 offset1:1
	s_waitcnt lgkmcnt(2)
	v_mul_f32_e32 v12, 0x3fb8aa3b, v4
	v_exp_f32_e32 v12, v12
	s_waitcnt lgkmcnt(1)
	v_mul_f32_e32 v10, 0x3fb8aa3b, v0
	v_sub_f32_e32 v52, v0, v2
	v_sub_f32_e32 v0, v2, v0
	v_mul_f32_e32 v0, 0x3fb8aa3b, v0
	v_exp_f32_e32 v0, v0
	v_mul_f32_e32 v52, 0x3fb8aa3b, v52
	v_exp_f32_e32 v10, v10
	v_exp_f32_e32 v52, v52
	v_mul_f32_e32 v53, v0, v24
	s_waitcnt lgkmcnt(0)
	v_sub_f32_e32 v0, v4, v50
	v_mul_f32_e32 v0, 0x3fb8aa3b, v0
	v_exp_f32_e32 v0, v0
	v_mul_f32_e32 v10, v49, v10
	v_mul_f32_e32 v12, v49, v12
	v_mul_f32_e32 v52, v49, v52
	v_mul_f32_e32 v49, v49, v0
	v_sub_f32_e32 v0, v50, v4
	v_mul_f32_e32 v0, 0x3fb8aa3b, v0
	v_exp_f32_e32 v0, v0
	v_mul_f32_e32 v2, 0x3fb8aa3b, v1
	v_exp_f32_e32 v2, v2
	v_mul_f32_e32 v4, v0, v24
	v_mul_f32_e32 v0, 0x3e000000, v16
	v_mul_f32_e32 v16, v0, v2
	v_mul_f32_e32 v2, 0x3fb8aa3b, v5
	v_exp_f32_e32 v2, v2
	s_nop 0
	v_mul_f32_e32 v24, v0, v2
	v_sub_f32_e32 v2, v1, v3
	v_sub_f32_e32 v1, v3, v1
	v_mul_f32_e32 v1, 0x3fb8aa3b, v1
	v_exp_f32_e32 v1, v1
	v_mul_f32_e32 v2, 0x3fb8aa3b, v2
	v_exp_f32_e32 v2, v2
	v_mul_f32_e32 v54, v1, v9
	v_sub_f32_e32 v1, v5, v51
	v_mul_f32_e32 v1, 0x3fb8aa3b, v1
	v_exp_f32_e32 v1, v1
	v_mul_f32_e32 v50, v0, v2
	v_mul_f32_e32 v55, v0, v1
	v_sub_f32_e32 v0, v51, v5
	v_mul_f32_e32 v0, 0x3fb8aa3b, v0
	v_exp_f32_e32 v0, v0
	s_nop 0
	v_mul_f32_e32 v5, v0, v9
	v_mul_lo_u32 v9, v170, s85
	v_cvt_pk_bf16_f32 v0, v23, v28
	v_cvt_pk_bf16_f32 v1, v32, v36
	v_cvt_pk_bf16_f32 v2, v44, v48
	v_cvt_pk_bf16_f32 v3, v10, v16
	v_add3_u32 v9, 0, v9, v176
	ds_write_b128 v9, v[0:3] offset:54272
	v_cvt_pk_bf16_f32 v0, v21, v27
	v_cvt_pk_bf16_f32 v1, v31, v35
	v_cvt_pk_bf16_f32 v2, v42, v47
	v_cvt_pk_bf16_f32 v3, v12, v24
	ds_write_b128 v9, v[0:3] offset:54400
	v_mul_lo_u32 v9, v170, s87
	v_cvt_pk_bf16_f32 v0, v19, v26
	v_cvt_pk_bf16_f32 v1, v30, v34
	v_cvt_pk_bf16_f32 v2, v40, v46
	v_cvt_pk_bf16_f32 v3, v52, v50
	v_add3_u32 v10, s86, v9, v176
	ds_write_b128 v10, v[0:3]
	v_cvt_pk_bf16_f32 v0, v18, v25
	v_cvt_pk_bf16_f32 v1, v29, v33
	v_cvt_pk_bf16_f32 v2, v39, v45
	v_cvt_pk_bf16_f32 v3, v53, v54
	v_add3_u32 v10, s88, v9, v176
	ds_write_b128 v10, v[0:3]
	v_cvt_pk_bf16_f32 v0, v17, v22
	v_cvt_pk_bf16_f32 v1, v14, v15
	v_cvt_pk_bf16_f32 v2, v38, v43
	v_cvt_pk_bf16_f32 v3, v49, v55
	v_add3_u32 v10, s89, v9, v176
	ds_write_b128 v10, v[0:3]
	v_cvt_pk_bf16_f32 v0, v13, v20
	v_cvt_pk_bf16_f32 v1, v6, v7
	v_cvt_pk_bf16_f32 v2, v37, v41
	v_cvt_pk_bf16_f32 v3, v4, v5
	v_add3_u32 v4, s52, v9, v176
	ds_write_b128 v4, v[0:3]
	v_lshl_add_u64 v[0:1], v[118:119], 0, s[8:9]
	v_mov_b32_e32 v9, v177
	v_lshl_add_u64 v[0:1], v[0:1], 0, v[8:9]
	v_lshl_add_u64 v[4:5], v[0:1], 0, s[0:1]
	v_add_co_u32_e64 v0, s[0:1], s92, v0
	v_lshlrev_b32_e32 v17, 1, v170
	s_nop 0
	v_addc_co_u32_e64 v1, s[0:1], 0, v1, s[0:1]
	global_load_dwordx4 v[0:3], v[0:1], off offset:2048
	s_nop 0
	global_load_dwordx4 v[4:7], v[4:5], off offset:16
	v_add3_u32 v11, s53, v17, v11
	s_lshl_b64 s[0:1], s[14:15], 18
	s_add_u32 s0, s56, s0
	s_addc_u32 s1, s57, s1
	s_or_b32 s2, s14, 1
	s_waitcnt vmcnt(1)
	v_lshlrev_b32_e32 v8, 16, v0
	v_and_b32_e32 v0, 0xffff0000, v0
	v_cvt_pk_bf16_f32 v8, v8, v177
	ds_write_b16 v11, v8
	v_cvt_pk_bf16_f32 v0, v0, v177
	v_lshlrev_b32_e32 v9, 16, v1
	ds_write_b16 v11, v0 offset:144
	v_cvt_pk_bf16_f32 v0, v9, v177
	v_and_b32_e32 v1, 0xffff0000, v1
	ds_write_b16 v11, v0 offset:288
	v_cvt_pk_bf16_f32 v0, v1, v177
	v_lshlrev_b32_e32 v10, 16, v2
	ds_write_b16 v11, v0 offset:432
	v_cvt_pk_bf16_f32 v0, v10, v177
	v_and_b32_e32 v2, 0xffff0000, v2
	ds_write_b16 v11, v0 offset:576
	v_cvt_pk_bf16_f32 v0, v2, v177
	v_lshlrev_b32_e32 v12, 16, v3
	ds_write_b16 v11, v0 offset:720
	v_cvt_pk_bf16_f32 v0, v12, v177
	v_and_b32_e32 v3, 0xffff0000, v3
	ds_write_b16 v11, v0 offset:864
	v_cvt_pk_bf16_f32 v0, v3, v177
	s_waitcnt vmcnt(0)
	v_lshlrev_b32_e32 v13, 16, v4
	ds_write_b16 v11, v0 offset:1008
	v_cvt_pk_bf16_f32 v0, v13, v177
	v_and_b32_e32 v4, 0xffff0000, v4
	ds_write_b16 v11, v0 offset:1152
	v_cvt_pk_bf16_f32 v0, v4, v177
	v_lshlrev_b32_e32 v14, 16, v5
	ds_write_b16 v11, v0 offset:1296
	v_cvt_pk_bf16_f32 v0, v14, v177
	v_and_b32_e32 v5, 0xffff0000, v5
	ds_write_b16 v11, v0 offset:1440
	v_cvt_pk_bf16_f32 v0, v5, v177
	v_lshlrev_b32_e32 v15, 16, v6
	ds_write_b16 v11, v0 offset:1584
	v_cvt_pk_bf16_f32 v0, v15, v177
	v_and_b32_e32 v6, 0xffff0000, v6
	ds_write_b16 v11, v0 offset:1728
	v_cvt_pk_bf16_f32 v0, v6, v177
	v_lshlrev_b32_e32 v16, 16, v7
	ds_write_b16 v11, v0 offset:1872
	v_cvt_pk_bf16_f32 v0, v16, v177
	v_and_b32_e32 v7, 0xffff0000, v7
	ds_write_b16 v11, v0 offset:2016
	v_cvt_pk_bf16_f32 v0, v7, v177
	ds_write_b16 v11, v0 offset:2160
	v_lshlrev_b32_e32 v0, 11, v171
	v_and_b32_e32 v2, 0x7800, v0
	v_mov_b32_e32 v3, v177
	v_lshl_add_u64 v[0:1], s[0:1], 0, v[2:3]
	s_lshl_b64 s[0:1], s[2:3], 18
	s_add_u32 s0, s56, s0
	s_addc_u32 s1, s57, s1
	v_lshl_add_u64 v[2:3], s[0:1], 0, v[2:3]
	s_cbranch_vccz .LBB0_659
	v_readlane_b32 s68, v254, 16
	v_readlane_b32 s69, v254, 17
	s_sub_i32 s70, s61, 64
	s_lshl_b32 s70, s70, 3
	s_or_b32 s70, s70, s55
	s_mov_b32 s71, 0
	s_lshl_b64 s[70:71], s[70:71], 16
	s_add_u32 s68, s68, s70
	s_addc_u32 s69, s69, s71
	s_add_u32 s70, s68, 0x8000
	s_addc_u32 s71, s69, 0
	v_lshlrev_b32_e32 v186, 4, v171
	global_load_dwordx4 v[132:135], v186, s[68:69]
	global_load_dwordx4 v[128:131], v186, s[70:71]
	v_add_u32_e32 v187, 0x2000, v186
	global_load_dwordx4 v[140:143], v187, s[68:69]
	global_load_dwordx4 v[136:139], v187, s[70:71]
	v_add_u32_e32 v187, 0x4000, v186
	global_load_dwordx4 v[148:151], v187, s[68:69]
	global_load_dwordx4 v[144:147], v187, s[70:71]
	v_add_u32_e32 v187, 0x6000, v186
	global_load_dwordx4 v[156:159], v187, s[68:69]
	global_load_dwordx4 v[152:155], v187, s[70:71]
	v_ashrrev_i32_e32 v117, 31, v116
	s_branch .LBB0_643
	v_ashrrev_i32_e32 v4, 4, v171
	v_ashrrev_i32_e32 v5, 31, v4
	v_lshlrev_b64 v[4:5], 2, v[4:5]
	v_lshl_add_u64 v[6:7], v[0:1], 0, v[4:5]
	v_lshl_add_u64 v[4:5], v[2:3], 0, v[4:5]
	global_load_dword v132, v[6:7], off
	global_load_dword v133, v[6:7], off offset:512
	global_load_dword v134, v[6:7], off offset:1024
	global_load_dword v135, v[6:7], off offset:1536
	global_load_dword v128, v[4:5], off
	global_load_dword v129, v[4:5], off offset:512
	global_load_dword v130, v[4:5], off offset:1024
	global_load_dword v131, v[4:5], off offset:1536
	v_cndmask_b32_e64 v4, 0, 1, s[24:25]
	v_cmp_ne_u32_e64 s[0:1], 1, v4
	s_andn2_b64 vcc, exec, s[24:25]
	s_cbranch_vccz .LBB0_660

.LBB0_1302:
	s_or_b64 exec, exec, s[0:1]
	v_readlane_b32 s0, v253, 14
	v_readlane_b32 s1, v253, 15
	s_and_b64 vcc, exec, s[0:1]
	s_waitcnt lgkmcnt(0)
	s_barrier
	s_cbranch_vccnz .LBB0_1434
	s_mov_b32 s63, s96
	s_cmpk_gt_u32 s63, 0xff
	s_cbranch_scc1 .Lps_done1
.Lps_loop1:
	s_and_b32 s0, s63, 7
	s_lshr_b32 s1, s63, 3
	s_lshr_b32 s2, s1, 4
	s_bfe_u32 s3, s1, 0x10003
	s_and_b32 s4, s1, 7
	s_lshl_b32 s5, s2, 5
	s_add_i32 s5, s5, 64
	s_mov_b32 s6, 0x80000
	s_movk_i32 s8, 0x1000
	s_cmp_eq_u32 s3, 0
	s_cselect_b32 s10, 0, 31
	s_cselect_b32 s6, s6, 0xfff80000
	s_cselect_b32 s7, 0, -1
	s_cselect_b32 s8, s8, 0xfffff000
	s_cselect_b32 s9, 0, -1
	s_add_i32 s5, s5, s10
	s_lshl_b32 s11, s5, 3
	s_or_b32 s11, s11, s0
	s_lshl_b32 s11, s11, 1
	s_or_b32 s11, s11, s3
	s_lshl_b32 s16, s4, 12
	s_mov_b32 s12, s11
	s_mov_b32 s13, 0
	s_lshl_b64 s[12:13], s[12:13], 15
	s_add_u32 s12, s12, s42
	s_addc_u32 s13, s13, s43
	s_add_u32 s12, s12, s16
	s_addc_u32 s13, s13, 0
	s_mov_b32 s14, s11
	s_mov_b32 s15, 0
	s_lshl_b64 s[14:15], s[14:15], 8
	s_add_u32 s14, s14, s44
	s_addc_u32 s15, s15, s45
	v_readlane_b32 s52, v254, 16
	v_readlane_b32 s53, v254, 17
	s_sub_i32 s54, s11, 0x400
	s_mov_b32 s55, 0
	s_lshl_b64 s[54:55], s[54:55], 15
	s_add_u32 s52, s52, s54
	s_addc_u32 s53, s53, s55
	s_add_u32 s52, s52, s16
	s_addc_u32 s53, s53, 0
	v_readlane_b32 s56, v254, 36
	v_readlane_b32 s57, v254, 37
	s_lshl_b32 s58, s2, 1
	s_or_b32 s58, s58, 1
	s_lshl_b32 s58, s58, 1
	s_or_b32 s58, s58, s3
	s_lshl_b32 s58, s58, 3
	s_or_b32 s58, s58, s0
	s_mov_b32 s59, 0
	s_lshl_b64 s[58:59], s[58:59], 15
	s_add_u32 s56, s56, s58
	s_addc_u32 s57, s57, s59
	s_lshl_b32 s58, s4, 6
	s_add_u32 s56, s56, s58
	s_addc_u32 s57, s57, 0
	v_lshlrev_b32_e32 v0, 3, v180
	v_mov_b32_e32 v1, 0
	v_and_b32_e32 v10, 31, v180
	v_lshlrev_b32_e32 v12, 10, v10
	v_lshlrev_b32_e32 v10, 3, v10
	v_mov_b32_e32 v11, 0
	v_lshrrev_b32_e32 v13, 5, v180
	v_lshl_add_u32 v12, v13, 2, v12
	global_load_dword v8, v12, s[56:57]
	global_load_dword v9, v12, s[56:57] offset:512
	v_lshl_add_u64 v[2:3], s[12:13], 0, v[0:1]
	v_lshl_add_u64 v[4:5], s[14:15], 0, v[10:11]
	v_lshl_add_u64 v[6:7], s[52:53], 0, v[0:1]
	global_load_dwordx2 v[16:17], v[2:3], off
	v_lshl_add_u64 v[2:3], v[2:3], 0, s[6:7]
	global_load_dwordx2 v[48:49], v[4:5], off
	v_lshl_add_u64 v[4:5], v[4:5], 0, s[8:9]
	global_load_dwordx2 v[18:19], v[2:3], off
	v_lshl_add_u64 v[2:3], v[2:3], 0, s[6:7]
	global_load_dwordx2 v[50:51], v[4:5], off
	v_lshl_add_u64 v[4:5], v[4:5], 0, s[8:9]
	global_load_dwordx2 v[20:21], v[2:3], off
	v_lshl_add_u64 v[2:3], v[2:3], 0, s[6:7]
	global_load_dwordx2 v[52:53], v[4:5], off
	v_lshl_add_u64 v[4:5], v[4:5], 0, s[8:9]
	global_load_dwordx2 v[22:23], v[2:3], off
	v_lshl_add_u64 v[2:3], v[2:3], 0, s[6:7]
	global_load_dwordx2 v[54:55], v[4:5], off
	v_lshl_add_u64 v[4:5], v[4:5], 0, s[8:9]
	global_load_dwordx2 v[24:25], v[2:3], off
	v_lshl_add_u64 v[2:3], v[2:3], 0, s[6:7]
	global_load_dwordx2 v[56:57], v[4:5], off
	v_lshl_add_u64 v[4:5], v[4:5], 0, s[8:9]
	global_load_dwordx2 v[26:27], v[2:3], off
	v_lshl_add_u64 v[2:3], v[2:3], 0, s[6:7]
	global_load_dwordx2 v[58:59], v[4:5], off
	v_lshl_add_u64 v[4:5], v[4:5], 0, s[8:9]
	global_load_dwordx2 v[28:29], v[2:3], off
	v_lshl_add_u64 v[2:3], v[2:3], 0, s[6:7]
	global_load_dwordx2 v[60:61], v[4:5], off
	v_lshl_add_u64 v[4:5], v[4:5], 0, s[8:9]
	global_load_dwordx2 v[30:31], v[2:3], off
	v_lshl_add_u64 v[2:3], v[2:3], 0, s[6:7]
	global_load_dwordx2 v[62:63], v[4:5], off
	v_lshl_add_u64 v[4:5], v[4:5], 0, s[8:9]
	global_load_dwordx2 v[32:33], v[2:3], off
	v_lshl_add_u64 v[2:3], v[2:3], 0, s[6:7]
	global_load_dwordx2 v[64:65], v[4:5], off
	v_lshl_add_u64 v[4:5], v[4:5], 0, s[8:9]
	global_load_dwordx2 v[34:35], v[2:3], off
	v_lshl_add_u64 v[2:3], v[2:3], 0, s[6:7]
	global_load_dwordx2 v[66:67], v[4:5], off
	v_lshl_add_u64 v[4:5], v[4:5], 0, s[8:9]
	global_load_dwordx2 v[36:37], v[2:3], off
	v_lshl_add_u64 v[2:3], v[2:3], 0, s[6:7]
	global_load_dwordx2 v[68:69], v[4:5], off
	v_lshl_add_u64 v[4:5], v[4:5], 0, s[8:9]
	global_load_dwordx2 v[38:39], v[2:3], off
	v_lshl_add_u64 v[2:3], v[2:3], 0, s[6:7]
	global_load_dwordx2 v[70:71], v[4:5], off
	v_lshl_add_u64 v[4:5], v[4:5], 0, s[8:9]
	global_load_dwordx2 v[40:41], v[2:3], off
	v_lshl_add_u64 v[2:3], v[2:3], 0, s[6:7]
	global_load_dwordx2 v[72:73], v[4:5], off
	v_lshl_add_u64 v[4:5], v[4:5], 0, s[8:9]
	global_load_dwordx2 v[42:43], v[2:3], off
	v_lshl_add_u64 v[2:3], v[2:3], 0, s[6:7]
	global_load_dwordx2 v[74:75], v[4:5], off
	v_lshl_add_u64 v[4:5], v[4:5], 0, s[8:9]
	global_load_dwordx2 v[44:45], v[2:3], off
	v_lshl_add_u64 v[2:3], v[2:3], 0, s[6:7]
	global_load_dwordx2 v[76:77], v[4:5], off
	v_lshl_add_u64 v[4:5], v[4:5], 0, s[8:9]
	global_load_dwordx2 v[46:47], v[2:3], off
	v_lshl_add_u64 v[2:3], v[2:3], 0, s[6:7]
	global_load_dwordx2 v[78:79], v[4:5], off
	v_lshl_add_u64 v[4:5], v[4:5], 0, s[8:9]
	s_waitcnt vmcnt(30)
	global_store_dwordx2 v[6:7], v[8:9], off
	v_lshl_add_u64 v[6:7], v[6:7], 0, s[6:7]
	v_pk_fma_f32 v[8:9], v[8:9], v[48:49], v[16:17]
	s_waitcnt vmcnt(29)
	global_store_dwordx2 v[6:7], v[8:9], off
	v_lshl_add_u64 v[6:7], v[6:7], 0, s[6:7]
	v_pk_fma_f32 v[8:9], v[8:9], v[50:51], v[18:19]
	s_waitcnt vmcnt(28)
	global_store_dwordx2 v[6:7], v[8:9], off
	v_lshl_add_u64 v[6:7], v[6:7], 0, s[6:7]
	v_pk_fma_f32 v[8:9], v[8:9], v[52:53], v[20:21]
	s_waitcnt vmcnt(27)
	global_store_dwordx2 v[6:7], v[8:9], off
	v_lshl_add_u64 v[6:7], v[6:7], 0, s[6:7]
	v_pk_fma_f32 v[8:9], v[8:9], v[54:55], v[22:23]
	s_waitcnt vmcnt(26)
	global_store_dwordx2 v[6:7], v[8:9], off
	v_lshl_add_u64 v[6:7], v[6:7], 0, s[6:7]
	v_pk_fma_f32 v[8:9], v[8:9], v[56:57], v[24:25]
	s_waitcnt vmcnt(25)
	global_store_dwordx2 v[6:7], v[8:9], off
	v_lshl_add_u64 v[6:7], v[6:7], 0, s[6:7]
	v_pk_fma_f32 v[8:9], v[8:9], v[58:59], v[26:27]
	s_waitcnt vmcnt(24)
	global_store_dwordx2 v[6:7], v[8:9], off
	v_lshl_add_u64 v[6:7], v[6:7], 0, s[6:7]
	v_pk_fma_f32 v[8:9], v[8:9], v[60:61], v[28:29]
	s_waitcnt vmcnt(23)
	global_store_dwordx2 v[6:7], v[8:9], off
	v_lshl_add_u64 v[6:7], v[6:7], 0, s[6:7]
	v_pk_fma_f32 v[8:9], v[8:9], v[62:63], v[30:31]
	s_waitcnt vmcnt(22)
	global_store_dwordx2 v[6:7], v[8:9], off
	v_lshl_add_u64 v[6:7], v[6:7], 0, s[6:7]
	v_pk_fma_f32 v[8:9], v[8:9], v[64:65], v[32:33]
	s_waitcnt vmcnt(21)
	global_store_dwordx2 v[6:7], v[8:9], off
	v_lshl_add_u64 v[6:7], v[6:7], 0, s[6:7]
	v_pk_fma_f32 v[8:9], v[8:9], v[66:67], v[34:35]
	s_waitcnt vmcnt(20)
	global_store_dwordx2 v[6:7], v[8:9], off
	v_lshl_add_u64 v[6:7], v[6:7], 0, s[6:7]
	v_pk_fma_f32 v[8:9], v[8:9], v[68:69], v[36:37]
	s_waitcnt vmcnt(19)
	global_store_dwordx2 v[6:7], v[8:9], off
	v_lshl_add_u64 v[6:7], v[6:7], 0, s[6:7]
	v_pk_fma_f32 v[8:9], v[8:9], v[70:71], v[38:39]
	s_waitcnt vmcnt(18)
	global_store_dwordx2 v[6:7], v[8:9], off
	v_lshl_add_u64 v[6:7], v[6:7], 0, s[6:7]
	v_pk_fma_f32 v[8:9], v[8:9], v[72:73], v[40:41]
	s_waitcnt vmcnt(17)
	global_store_dwordx2 v[6:7], v[8:9], off
	v_lshl_add_u64 v[6:7], v[6:7], 0, s[6:7]
	v_pk_fma_f32 v[8:9], v[8:9], v[74:75], v[42:43]
	s_waitcnt vmcnt(16)
	global_store_dwordx2 v[6:7], v[8:9], off
	v_lshl_add_u64 v[6:7], v[6:7], 0, s[6:7]
	v_pk_fma_f32 v[8:9], v[8:9], v[76:77], v[44:45]
	s_waitcnt vmcnt(15)
	global_store_dwordx2 v[6:7], v[8:9], off
	v_lshl_add_u64 v[6:7], v[6:7], 0, s[6:7]
	v_pk_fma_f32 v[8:9], v[8:9], v[78:79], v[46:47]
	global_load_dwordx2 v[16:17], v[2:3], off
	v_lshl_add_u64 v[2:3], v[2:3], 0, s[6:7]
	global_load_dwordx2 v[48:49], v[4:5], off
	v_lshl_add_u64 v[4:5], v[4:5], 0, s[8:9]
	global_load_dwordx2 v[18:19], v[2:3], off
	v_lshl_add_u64 v[2:3], v[2:3], 0, s[6:7]
	global_load_dwordx2 v[50:51], v[4:5], off
	v_lshl_add_u64 v[4:5], v[4:5], 0, s[8:9]
	global_load_dwordx2 v[20:21], v[2:3], off
	v_lshl_add_u64 v[2:3], v[2:3], 0, s[6:7]
	global_load_dwordx2 v[52:53], v[4:5], off
	v_lshl_add_u64 v[4:5], v[4:5], 0, s[8:9]
	global_load_dwordx2 v[22:23], v[2:3], off
	v_lshl_add_u64 v[2:3], v[2:3], 0, s[6:7]
	global_load_dwordx2 v[54:55], v[4:5], off
	v_lshl_add_u64 v[4:5], v[4:5], 0, s[8:9]
	global_load_dwordx2 v[24:25], v[2:3], off
	v_lshl_add_u64 v[2:3], v[2:3], 0, s[6:7]
	global_load_dwordx2 v[56:57], v[4:5], off
	v_lshl_add_u64 v[4:5], v[4:5], 0, s[8:9]
	global_load_dwordx2 v[26:27], v[2:3], off
	v_lshl_add_u64 v[2:3], v[2:3], 0, s[6:7]
	global_load_dwordx2 v[58:59], v[4:5], off
	v_lshl_add_u64 v[4:5], v[4:5], 0, s[8:9]
	global_load_dwordx2 v[28:29], v[2:3], off
	v_lshl_add_u64 v[2:3], v[2:3], 0, s[6:7]
	global_load_dwordx2 v[60:61], v[4:5], off
	v_lshl_add_u64 v[4:5], v[4:5], 0, s[8:9]
	global_load_dwordx2 v[30:31], v[2:3], off
	v_lshl_add_u64 v[2:3], v[2:3], 0, s[6:7]
	global_load_dwordx2 v[62:63], v[4:5], off
	v_lshl_add_u64 v[4:5], v[4:5], 0, s[8:9]
	global_load_dwordx2 v[32:33], v[2:3], off
	v_lshl_add_u64 v[2:3], v[2:3], 0, s[6:7]
	global_load_dwordx2 v[64:65], v[4:5], off
	v_lshl_add_u64 v[4:5], v[4:5], 0, s[8:9]
	global_load_dwordx2 v[34:35], v[2:3], off
	v_lshl_add_u64 v[2:3], v[2:3], 0, s[6:7]
	global_load_dwordx2 v[66:67], v[4:5], off
	v_lshl_add_u64 v[4:5], v[4:5], 0, s[8:9]
	global_load_dwordx2 v[36:37], v[2:3], off
	v_lshl_add_u64 v[2:3], v[2:3], 0, s[6:7]
	global_load_dwordx2 v[68:69], v[4:5], off
	v_lshl_add_u64 v[4:5], v[4:5], 0, s[8:9]
	global_load_dwordx2 v[38:39], v[2:3], off
	v_lshl_add_u64 v[2:3], v[2:3], 0, s[6:7]
	global_load_dwordx2 v[70:71], v[4:5], off
	v_lshl_add_u64 v[4:5], v[4:5], 0, s[8:9]
	global_load_dwordx2 v[40:41], v[2:3], off
	v_lshl_add_u64 v[2:3], v[2:3], 0, s[6:7]
	global_load_dwordx2 v[72:73], v[4:5], off
	v_lshl_add_u64 v[4:5], v[4:5], 0, s[8:9]
	global_load_dwordx2 v[42:43], v[2:3], off
	v_lshl_add_u64 v[2:3], v[2:3], 0, s[6:7]
	global_load_dwordx2 v[74:75], v[4:5], off
	v_lshl_add_u64 v[4:5], v[4:5], 0, s[8:9]
	global_load_dwordx2 v[44:45], v[2:3], off
	v_lshl_add_u64 v[2:3], v[2:3], 0, s[6:7]
	global_load_dwordx2 v[76:77], v[4:5], off
	v_lshl_add_u64 v[4:5], v[4:5], 0, s[8:9]
	global_load_dwordx2 v[46:47], v[2:3], off
	v_lshl_add_u64 v[2:3], v[2:3], 0, s[6:7]
	global_load_dwordx2 v[78:79], v[4:5], off
	v_lshl_add_u64 v[4:5], v[4:5], 0, s[8:9]
	s_waitcnt vmcnt(30)
	global_store_dwordx2 v[6:7], v[8:9], off
	v_lshl_add_u64 v[6:7], v[6:7], 0, s[6:7]
	v_pk_fma_f32 v[8:9], v[8:9], v[48:49], v[16:17]
	s_waitcnt vmcnt(29)
	global_store_dwordx2 v[6:7], v[8:9], off
	v_lshl_add_u64 v[6:7], v[6:7], 0, s[6:7]
	v_pk_fma_f32 v[8:9], v[8:9], v[50:51], v[18:19]
	s_waitcnt vmcnt(28)
	global_store_dwordx2 v[6:7], v[8:9], off
	v_lshl_add_u64 v[6:7], v[6:7], 0, s[6:7]
	v_pk_fma_f32 v[8:9], v[8:9], v[52:53], v[20:21]
	s_waitcnt vmcnt(27)
	global_store_dwordx2 v[6:7], v[8:9], off
	v_lshl_add_u64 v[6:7], v[6:7], 0, s[6:7]
	v_pk_fma_f32 v[8:9], v[8:9], v[54:55], v[22:23]
	s_waitcnt vmcnt(26)
	global_store_dwordx2 v[6:7], v[8:9], off
	v_lshl_add_u64 v[6:7], v[6:7], 0, s[6:7]
	v_pk_fma_f32 v[8:9], v[8:9], v[56:57], v[24:25]
	s_waitcnt vmcnt(25)
	global_store_dwordx2 v[6:7], v[8:9], off
	v_lshl_add_u64 v[6:7], v[6:7], 0, s[6:7]
	v_pk_fma_f32 v[8:9], v[8:9], v[58:59], v[26:27]
	s_waitcnt vmcnt(24)
	global_store_dwordx2 v[6:7], v[8:9], off
	v_lshl_add_u64 v[6:7], v[6:7], 0, s[6:7]
	v_pk_fma_f32 v[8:9], v[8:9], v[60:61], v[28:29]
	s_waitcnt vmcnt(23)
	global_store_dwordx2 v[6:7], v[8:9], off
	v_lshl_add_u64 v[6:7], v[6:7], 0, s[6:7]
	v_pk_fma_f32 v[8:9], v[8:9], v[62:63], v[30:31]
	s_waitcnt vmcnt(22)
	global_store_dwordx2 v[6:7], v[8:9], off
	v_lshl_add_u64 v[6:7], v[6:7], 0, s[6:7]
	v_pk_fma_f32 v[8:9], v[8:9], v[64:65], v[32:33]
	s_waitcnt vmcnt(21)
	global_store_dwordx2 v[6:7], v[8:9], off
	v_lshl_add_u64 v[6:7], v[6:7], 0, s[6:7]
	v_pk_fma_f32 v[8:9], v[8:9], v[66:67], v[34:35]
	s_waitcnt vmcnt(20)
	global_store_dwordx2 v[6:7], v[8:9], off
	v_lshl_add_u64 v[6:7], v[6:7], 0, s[6:7]
	v_pk_fma_f32 v[8:9], v[8:9], v[68:69], v[36:37]
	s_waitcnt vmcnt(19)
	global_store_dwordx2 v[6:7], v[8:9], off
	v_lshl_add_u64 v[6:7], v[6:7], 0, s[6:7]
	v_pk_fma_f32 v[8:9], v[8:9], v[70:71], v[38:39]
	s_waitcnt vmcnt(18)
	global_store_dwordx2 v[6:7], v[8:9], off
	v_lshl_add_u64 v[6:7], v[6:7], 0, s[6:7]
	v_pk_fma_f32 v[8:9], v[8:9], v[72:73], v[40:41]
	s_waitcnt vmcnt(17)
	global_store_dwordx2 v[6:7], v[8:9], off
	v_lshl_add_u64 v[6:7], v[6:7], 0, s[6:7]
	v_pk_fma_f32 v[8:9], v[8:9], v[74:75], v[42:43]
	s_waitcnt vmcnt(16)
	global_store_dwordx2 v[6:7], v[8:9], off
	v_lshl_add_u64 v[6:7], v[6:7], 0, s[6:7]
	v_pk_fma_f32 v[8:9], v[8:9], v[76:77], v[44:45]
	s_waitcnt vmcnt(15)
	global_store_dwordx2 v[6:7], v[8:9], off
	v_lshl_add_u64 v[6:7], v[6:7], 0, s[6:7]
	v_pk_fma_f32 v[8:9], v[8:9], v[78:79], v[46:47]
	s_add_i32 s63, s63, s94
	s_cmpk_lt_u32 s63, 0x100
	s_cbranch_scc1 .Lps_loop1
.Lps_done1:
	s_waitcnt vmcnt(0)
	s_barrier
	v_cmp_eq_u32_e64 s[10:11], 0, v180
	s_and_saveexec_b64 s[12:13], s[10:11]
	s_cbranch_execz .Lps_arrived1
	buffer_wbl2 sc1
	s_waitcnt vmcnt(0)
	v_readlane_b32 s14, v254, 2
	v_readlane_b32 s15, v254, 3
	v_mov_b32_e32 v0, 0
	v_mov_b32_e32 v1, 1
	s_nop 4
	global_atomic_add v0, v1, s[14:15] offset:20
.Lps_arrived1:
	s_or_b64 exec, exec, s[12:13]
	v_readlane_b32 s4, v254, 60
	v_readlane_b32 s11, v253, 3
	v_readlane_b32 s14, v253, 6
	v_readlane_b32 s9, v253, 1
	v_readlane_b32 s10, v253, 2
	v_readlane_b32 s15, v253, 7
	s_add_u32 s11, s14, 0x8040000
	s_addc_u32 s33, s15, 0
	s_mov_b32 s9, 0
	s_movk_i32 s34, 0x1000
	s_movk_i32 s35, 0x80
	v_mov_b32_e32 v177, 0
	s_mov_b32 s38, 0x42b504f3
	v_mov_b32_e32 v182, 0xf149f2ca
	s_mov_b32 s10, 0x3e0293ee
	s_movk_i32 s39, 0xfefe
	s_movk_i32 s52, 0x5040
	s_movk_i32 s53, 0x110
	s_add_i32 s54, 0, 0x11800
	s_movk_i32 s55, 0x90
	s_add_i32 s56, 0, 0x13c00
	s_add_i32 s57, 0, 0x16000
	s_add_i32 s58, 0, 0x18400
	s_add_i32 s59, 0, 0x1a800
	v_mbcnt_hi_u32_b32 v183, -1, v181
	v_mov_b32_e32 v184, 0x358637bd
	v_mov_b32_e32 v185, 0x80
	s_mov_b32 s60, s96
	v_readlane_b32 s5, v254, 61
	v_readlane_b32 s6, v254, 62
	v_readlane_b32 s7, v254, 63
	v_readlane_b32 s8, v253, 0
	v_readlane_b32 s12, v253, 4
	v_readlane_b32 s13, v253, 5
	v_readlane_b32 s16, v253, 8
	v_readlane_b32 s17, v253, 9
	v_readlane_b32 s18, v253, 10
	v_readlane_b32 s19, v253, 11
	s_branch .LBB0_1305

.LBB0_1353:
	v_cmp_eq_u32_e64 s[0:1], 0, v180
	s_and_saveexec_b64 s[2:3], s[0:1]
	s_cbranch_execz .Lpw_done1
	v_readlane_b32 s4, v254, 2
	v_readlane_b32 s5, v254, 3
	v_mov_b32_e32 v0, 0
	s_mov_b32 s12, 0
	s_min_u32 s14, s94, 0x100
	s_nop 4
.Lpw_spin1:
	global_load_dword v1, v0, s[4:5] offset:20 sc1
	s_waitcnt vmcnt(0)
	v_readfirstlane_b32 s13, v1
	s_cmp_ge_u32 s13, s14
	s_cbranch_scc1 .Lpw_ok1
	s_add_u32 s12, s12, 1
	s_cmp_gt_u32 s12, 0x8000
	s_cbranch_scc1 .Lpw_ok1
	s_sleep 1
	s_branch .Lpw_spin1

.Lpw_done1:
	s_or_b64 exec, exec, s[2:3]
	s_barrier
	v_readlane_b32 s64, v254, 28
	s_and_b32 s24, s60, 7
	v_readlane_b32 s72, v254, 36
	v_readlane_b32 s73, v254, 37
	s_lshl_b32 s0, s24, 6
	s_lshl_b32 s1, s24, 7
	s_lshl_b32 s2, s24, 15
	s_mov_b64 s[16:17], s[72:73]
	s_add_u32 s25, s16, s2
	v_readlane_b32 s65, v254, 29
	v_readlane_b32 s66, v254, 30
	v_readlane_b32 s67, v254, 31
	v_readlane_b32 s68, v254, 32
	v_readlane_b32 s69, v254, 33
	v_readlane_b32 s70, v254, 34
	v_readlane_b32 s71, v254, 35
	v_readlane_b32 s74, v254, 38
	v_readlane_b32 s75, v254, 39
	v_readlane_b32 s76, v254, 40
	v_readlane_b32 s77, v254, 41
	v_readlane_b32 s78, v254, 42
	v_readlane_b32 s79, v254, 43
	s_addc_u32 s26, s17, 0
	s_add_u32 s27, s11, s2
	v_readlane_b32 s64, v254, 12
	s_addc_u32 s28, s33, 0
	s_lshl_b32 s2, s24, 8
	v_readlane_b32 s72, v254, 20
	v_readlane_b32 s73, v254, 21
	s_add_u32 s4, s72, s2
	s_addc_u32 s5, s73, 0
	s_mov_b32 s29, 0
	s_lshl_b32 s6, s0, 1
	s_lshl_b32 s8, s1, 1
	v_readlane_b32 s65, v254, 13
	v_readlane_b32 s66, v254, 14
	v_readlane_b32 s67, v254, 15
	v_readlane_b32 s68, v254, 16
	v_readlane_b32 s69, v254, 17
	v_readlane_b32 s70, v254, 18
	v_readlane_b32 s71, v254, 19
	v_readlane_b32 s74, v254, 22
	v_readlane_b32 s75, v254, 23
	v_readlane_b32 s76, v254, 24
	v_readlane_b32 s77, v254, 25
	v_readlane_b32 s78, v254, 26
	v_readlane_b32 s79, v254, 27
	s_branch .LBB0_1355

.LBB0_1355:
	s_lshl_b32 s0, s29, 8
	s_add_i32 s12, s0, s60
	s_mul_i32 s0, s12, 0x8200
	v_mov_b32_e32 v171, v180
	s_mul_hi_i32 s1, s12, 0x8200
	s_add_u32 s0, s46, s0
	s_movk_i32 s2, 0x820
	s_addc_u32 s1, s47, s1
	v_lshlrev_b32_e32 v120, 2, v171
	v_lshlrev_b32_e32 v186, 4, v171
	v_ashrrev_i32_e32 v121, 31, v120
	global_load_dwordx4 v[188:191], v186, s[0:1]
	v_add_u32_e32 v172, 0x200, v171
	v_add_u32_e32 v187, 0x2000, v186
	v_lshlrev_b32_e32 v126, 2, v172
	global_load_dwordx4 v[192:195], v187, s[0:1]
	v_add_u32_e32 v173, 0x400, v171
	v_add_u32_e32 v187, 0x4000, v186
	v_lshlrev_b32_e32 v124, 2, v173
	global_load_dwordx4 v[196:199], v187, s[0:1]
	v_add_u32_e32 v174, 0x600, v171
	v_add_u32_e32 v187, 0x6000, v186
	v_lshlrev_b32_e32 v122, 2, v174
	global_load_dwordx4 v[200:203], v187, s[0:1]
	v_cmp_gt_i32_e32 vcc, 32, v171
	v_add_u32_e32 v187, 0x8000, v186
	s_nop 1
	v_cndmask_b32_e32 v187, 0, v187, vcc
	global_load_dwordx4 v[204:207], v187, s[0:1]
	s_ashr_i32 s61, s12, 3
	v_readlane_b32 s64, v254, 12
	s_lshl_b32 s0, s61, 6
	v_ashrrev_i32_e32 v170, 3, v171
	v_readlane_b32 s70, v254, 18
	v_readlane_b32 s71, v254, 19
	v_add_u32_e32 v116, s0, v170
	v_and_b32_e32 v19, 7, v171
	v_mov_b64_e32 v[0:1], s[70:71]
	v_mad_i64_i32 v[118:119], s[2:3], v116, s52, v[0:1]
	s_mov_b32 s7, s9
	v_lshl_add_u64 v[0:1], v[118:119], 0, s[6:7]
	v_lshlrev_b32_e32 v176, 4, v19
	v_lshl_add_u64 v[0:1], v[0:1], 0, v[176:177]
	v_add_co_u32_e32 v0, vcc, s34, v0
	s_nop 1
	v_addc_co_u32_e32 v1, vcc, 0, v1, vcc
	global_load_dwordx4 v[4:7], v[0:1], off
	global_load_dwordx4 v[8:11], v[0:1], off offset:1024
	s_waitcnt vmcnt(2)
	ds_write_b128 v186, v[188:191]
	ds_write_b128 v186, v[192:195] offset:8192
	ds_write_b128 v186, v[196:199] offset:16384
	ds_write_b128 v186, v[200:203] offset:24576
	v_cmp_gt_i32_e64 s[98:99], 32, v171
	s_and_saveexec_b64 s[62:63], s[98:99]
	ds_write_b128 v186, v[204:207] offset:32768
	s_mov_b64 exec, s[62:63]
	s_waitcnt lgkmcnt(0)
	s_barrier
	v_lshlrev_b32_e32 v16, 5, v19
	v_add_u32_e32 v18, 0, v16
	ds_read_b128 v[12:15], v18 offset:8320
	ds_read_b128 v[0:3], v18 offset:8336
	s_movk_i32 s1, 0x104
	v_mad_u64_u32 v[20:21], s[2:3], v170, s1, v[18:19]
	v_add_u32_e32 v21, 0x6084, v18
	v_add_u32_e32 v17, 0x607c, v18
	v_add_u32_e32 v30, 0x4100, v20
	v_add_u32_e32 v31, 0x4108, v20
	ds_read2_b32 v[28:29], v20 offset1:1
	ds_read2_b32 v[26:27], v20 offset0:2 offset1:3
	ds_read2_b32 v[24:25], v20 offset0:4 offset1:5
	ds_read2_b32 v[22:23], v20 offset0:6 offset1:7
	ds_read2_b32 v[32:33], v30 offset1:1
	ds_read2_b32 v[34:35], v17 offset1:1
	ds_read2_b32 v[40:41], v31 offset1:1
	ds_read2_b32 v[42:43], v21 offset1:1
	s_waitcnt lgkmcnt(7)
	v_sub_f32_e32 v21, v28, v12
	v_sub_f32_e32 v12, v12, v28
	v_mul_f32_e32 v12, 0x3fb8aa3b, v12
	v_exp_f32_e32 v12, v12
	v_mul_f32_e32 v17, 0x3fb8aa3b, v28
	v_mul_f32_e32 v28, 0x3fb8aa3b, v29
	v_sub_f32_e32 v30, v29, v13
	v_sub_f32_e32 v37, v13, v29
	v_exp_f32_e32 v13, v17
	s_waitcnt lgkmcnt(3)
	v_mul_f32_e32 v17, 0x3fb8aa3b, v32
	s_waitcnt lgkmcnt(2)
	v_sub_f32_e32 v29, v32, v34
	v_sub_f32_e32 v31, v34, v32
	v_exp_f32_e32 v32, v28
	v_mul_f32_e32 v21, 0x3fb8aa3b, v21
	v_mul_f32_e32 v30, 0x3fb8aa3b, v30
	v_mul_f32_e32 v29, 0x3fb8aa3b, v29
	v_mul_f32_e32 v31, 0x3fb8aa3b, v31
	v_exp_f32_e32 v21, v21
	v_exp_f32_e32 v30, v30
	v_exp_f32_e32 v38, v29
	v_exp_f32_e32 v29, v31
	v_mul_f32_e32 v28, 0x3fb8aa3b, v33
	v_exp_f32_e32 v17, v17
	v_exp_f32_e32 v34, v28
	s_mov_b64 s[2:3], 0x1800
	s_cmp_lt_i32 s61, 64
	s_mov_b32 s17, s9
	s_mov_b32 s15, s9
	v_readlane_b32 s65, v254, 13
	v_readlane_b32 s66, v254, 14
	v_readlane_b32 s67, v254, 15
	v_readlane_b32 s68, v254, 16
	v_readlane_b32 s69, v254, 17
	v_readlane_b32 s72, v254, 20
	v_readlane_b32 s73, v254, 21
	v_readlane_b32 s74, v254, 22
	v_readlane_b32 s75, v254, 23
	v_readlane_b32 s76, v254, 24
	v_readlane_b32 s77, v254, 25
	v_readlane_b32 s78, v254, 26
	v_readlane_b32 s79, v254, 27
	s_waitcnt vmcnt(1)
	v_lshlrev_b32_e32 v46, 16, v6
	v_and_b32_e32 v47, 0xffff0000, v6
	s_waitcnt vmcnt(0)
	v_lshlrev_b32_e32 v6, 16, v8
	v_lshlrev_b32_e32 v31, 16, v4
	v_and_b32_e32 v4, 0xffff0000, v4
	v_and_b32_e32 v45, 0xffff0000, v8
	v_mul_f32_e32 v8, v12, v6
	v_sub_f32_e32 v12, v35, v33
	v_lshlrev_b32_e32 v49, 16, v9
	v_and_b32_e32 v50, 0xffff0000, v9
	v_mul_f32_e32 v4, 0x3e000000, v4
	v_mul_f32_e32 v9, 0x3fb8aa3b, v37
	v_mul_f32_e32 v12, 0x3fb8aa3b, v12
	v_lshlrev_b32_e32 v48, 16, v7
	v_and_b32_e32 v36, 0xffff0000, v7
	v_lshlrev_b32_e32 v51, 16, v10
	v_and_b32_e32 v52, 0xffff0000, v10
	v_mul_f32_e32 v7, 0x3e000000, v31
	v_mul_f32_e32 v31, v4, v32
	v_exp_f32_e32 v9, v9
	v_sub_f32_e32 v10, v33, v35
	v_exp_f32_e32 v32, v12
	v_mul_f32_e32 v10, 0x3fb8aa3b, v10
	v_sub_f32_e32 v33, v26, v14
	v_sub_f32_e32 v14, v14, v26
	v_lshlrev_b32_e32 v39, 16, v11
	v_and_b32_e32 v28, 0xffff0000, v11
	v_mul_f32_e32 v11, v7, v21
	v_exp_f32_e32 v10, v10
	v_mul_f32_e32 v21, v4, v30
	v_mul_f32_e32 v30, 0x3fb8aa3b, v26
	v_mul_f32_e32 v14, 0x3fb8aa3b, v14
	v_exp_f32_e32 v30, v30
	v_exp_f32_e32 v14, v14
	v_mul_f32_e32 v12, v9, v45
	v_mul_f32_e32 v9, v32, v45
	s_waitcnt lgkmcnt(1)
	v_mul_f32_e32 v32, 0x3fb8aa3b, v40
	v_mul_f32_e32 v33, 0x3fb8aa3b, v33
	v_lshlrev_b32_e32 v44, 16, v5
	v_exp_f32_e32 v32, v32
	v_exp_f32_e32 v35, v33
	v_mul_f32_e32 v6, v29, v6
	v_mul_f32_e32 v29, v7, v13
	v_mul_f32_e32 v13, v7, v17
	v_mul_f32_e32 v17, v4, v34
	v_mul_f32_e32 v10, v4, v10
	v_mul_f32_e32 v4, 0x3e000000, v44
	v_mul_f32_e32 v34, v4, v30
	v_mul_f32_e32 v30, v14, v49
	s_waitcnt lgkmcnt(0)
	v_sub_f32_e32 v14, v40, v42
	v_sub_f32_e32 v26, v42, v40
	v_mul_f32_e32 v14, 0x3fb8aa3b, v14
	v_mul_f32_e32 v26, 0x3fb8aa3b, v26
	v_mul_f32_e32 v33, v4, v32
	v_mul_f32_e32 v32, v4, v35
	v_exp_f32_e32 v14, v14
	v_exp_f32_e32 v35, v26
	v_mul_f32_e32 v26, 0x3fb8aa3b, v27
	v_and_b32_e32 v5, 0xffff0000, v5
	v_exp_f32_e32 v37, v26
	v_mul_f32_e32 v26, v4, v14
	v_mul_f32_e32 v14, v35, v49
	v_sub_f32_e32 v35, v27, v15
	v_sub_f32_e32 v15, v15, v27
	v_sub_f32_e32 v27, v41, v43
	v_mul_f32_e32 v4, 0x3e000000, v5
	v_mul_f32_e32 v5, 0x3fb8aa3b, v41
	v_mul_f32_e32 v35, 0x3fb8aa3b, v35
	v_mul_f32_e32 v15, 0x3fb8aa3b, v15
	v_mul_f32_e32 v27, 0x3fb8aa3b, v27
	v_exp_f32_e32 v5, v5
	v_exp_f32_e32 v35, v35
	v_exp_f32_e32 v15, v15
	v_exp_f32_e32 v40, v27
	v_mul_f32_e32 v7, v7, v38
	v_mul_f32_e32 v37, v4, v37
	v_mul_f32_e32 v38, v4, v5
	v_mul_f32_e32 v35, v4, v35
	v_mul_f32_e32 v27, v15, v50
	v_mul_f32_e32 v15, v4, v40
	v_sub_f32_e32 v4, v43, v41
	v_mul_f32_e32 v4, 0x3fb8aa3b, v4
	v_exp_f32_e32 v49, v4
	v_add_u32_e32 v4, 0x4110, v20
	ds_read2_b32 v[4:5], v4 offset1:1
	v_add_u32_e32 v40, 0x608c, v18
	v_mul_f32_e32 v41, 0x3fb8aa3b, v24
	v_exp_f32_e32 v53, v41
	v_add_u32_e32 v20, 0x4118, v20
	v_add_u32_e32 v18, 0x6094, v18
	ds_read2_b32 v[40:41], v40 offset1:1
	ds_read2_b32 v[42:43], v20 offset1:1
	ds_read2_b32 v[44:45], v18 offset1:1
	s_waitcnt lgkmcnt(3)
	v_mul_f32_e32 v18, 0x3fb8aa3b, v4
	v_mul_f32_e32 v20, v49, v50
	v_sub_f32_e32 v50, v24, v0
	v_sub_f32_e32 v0, v0, v24
	s_waitcnt lgkmcnt(2)
	v_sub_f32_e32 v24, v4, v40
	v_sub_f32_e32 v4, v40, v4
	v_mul_f32_e32 v50, 0x3fb8aa3b, v50
	v_mul_f32_e32 v0, 0x3fb8aa3b, v0
	v_mul_f32_e32 v4, 0x3fb8aa3b, v4
	v_exp_f32_e32 v50, v50
	v_exp_f32_e32 v0, v0
	v_mul_f32_e32 v24, 0x3fb8aa3b, v24
	v_exp_f32_e32 v4, v4
	v_exp_f32_e32 v18, v18
	v_exp_f32_e32 v24, v24
	v_mul_f32_e32 v46, 0x3e000000, v46
	v_mul_f32_e32 v40, v46, v50
	v_mul_f32_e32 v50, v0, v51
	v_mul_f32_e32 v4, v4, v51
	v_sub_f32_e32 v51, v25, v1
	v_sub_f32_e32 v1, v1, v25
	v_mul_f32_e32 v49, v46, v53
	v_mul_f32_e32 v18, v46, v18
	v_mul_f32_e32 v24, v46, v24
	v_mul_f32_e32 v0, 0x3e000000, v47
	v_mul_f32_e32 v46, 0x3fb8aa3b, v25
	v_mul_f32_e32 v47, 0x3fb8aa3b, v5
	v_mul_f32_e32 v51, 0x3fb8aa3b, v51
	v_mul_f32_e32 v1, 0x3fb8aa3b, v1
	v_exp_f32_e32 v46, v46
	v_exp_f32_e32 v47, v47
	v_exp_f32_e32 v51, v51
	v_exp_f32_e32 v1, v1
	v_mul_f32_e32 v25, v0, v46
	v_mul_f32_e32 v46, v0, v47
	v_mul_f32_e32 v47, v0, v51
	v_mul_f32_e32 v51, v1, v52
	v_sub_f32_e32 v1, v5, v41
	v_mul_f32_e32 v1, 0x3fb8aa3b, v1
	v_exp_f32_e32 v1, v1
	v_sub_f32_e32 v5, v41, v5
	v_mul_f32_e32 v41, 0x3fb8aa3b, v22
	v_mul_f32_e32 v5, 0x3fb8aa3b, v5
	v_mul_f32_e32 v53, v0, v1
	v_mul_f32_e32 v0, 0x3e000000, v48
	v_sub_f32_e32 v48, v22, v2
	v_sub_f32_e32 v2, v2, v22
	s_waitcnt lgkmcnt(0)
	v_sub_f32_e32 v22, v42, v44
	v_mul_f32_e32 v1, 0x3fb8aa3b, v42
	v_mul_f32_e32 v48, 0x3fb8aa3b, v48
	v_mul_f32_e32 v22, 0x3fb8aa3b, v22
	v_exp_f32_e32 v5, v5
	v_exp_f32_e32 v41, v41
	v_exp_f32_e32 v1, v1
	v_exp_f32_e32 v48, v48
	v_exp_f32_e32 v22, v22
	v_mul_f32_e32 v2, 0x3fb8aa3b, v2
	v_exp_f32_e32 v2, v2
	v_mul_f32_e32 v5, v5, v52
	v_mul_f32_e32 v41, v0, v41
	v_mul_f32_e32 v52, v0, v1
	v_mul_f32_e32 v48, v0, v48
	v_mul_f32_e32 v22, v0, v22
	v_sub_f32_e32 v0, v44, v42
	v_mul_f32_e32 v0, 0x3fb8aa3b, v0
	v_mul_f32_e32 v54, v2, v39
	v_exp_f32_e32 v0, v0
	v_mul_f32_e32 v1, 0x3fb8aa3b, v23
	v_mul_f32_e32 v2, 0x3fb8aa3b, v43
	v_exp_f32_e32 v1, v1
	v_exp_f32_e32 v2, v2
	v_mul_f32_e32 v39, v0, v39
	v_mul_f32_e32 v0, 0x3e000000, v36
	v_mul_f32_e32 v36, v0, v1
	v_mul_f32_e32 v42, v0, v2
	v_sub_f32_e32 v1, v23, v3
	v_sub_f32_e32 v2, v3, v23
	v_sub_f32_e32 v3, v43, v45
	v_mul_f32_e32 v1, 0x3fb8aa3b, v1
	v_mul_f32_e32 v2, 0x3fb8aa3b, v2
	v_mul_f32_e32 v3, 0x3fb8aa3b, v3
	v_exp_f32_e32 v1, v1
	v_exp_f32_e32 v2, v2
	v_exp_f32_e32 v3, v3
	v_sub_f32_e32 v23, v45, v43
	v_mul_f32_e32 v43, v0, v1
	v_mul_f32_e32 v44, v2, v28
	v_mul_f32_e32 v45, v0, v3
	v_cvt_pk_bf16_f32 v0, v29, v31
	v_cvt_pk_bf16_f32 v1, v34, v37
	v_cvt_pk_bf16_f32 v2, v49, v25
	v_mul_lo_u32 v25, v170, s53
	v_add3_u32 v25, 0, v25, v176
	v_cvt_pk_bf16_f32 v3, v41, v36
	ds_write_b128 v25, v[0:3] offset:54272
	v_cvt_pk_bf16_f32 v0, v13, v17
	v_cvt_pk_bf16_f32 v1, v33, v38
	v_cvt_pk_bf16_f32 v2, v18, v46
	v_mul_lo_u32 v13, v170, s55
	v_cvt_pk_bf16_f32 v3, v52, v42
	ds_write_b128 v25, v[0:3] offset:54400
	v_cvt_pk_bf16_f32 v0, v11, v21
	v_cvt_pk_bf16_f32 v1, v32, v35
	v_cvt_pk_bf16_f32 v2, v40, v47
	v_add3_u32 v11, s54, v13, v176
	v_cvt_pk_bf16_f32 v3, v48, v43
	ds_write_b128 v11, v[0:3]
	v_cvt_pk_bf16_f32 v0, v8, v12
	v_cvt_pk_bf16_f32 v1, v30, v27
	v_cvt_pk_bf16_f32 v2, v50, v51
	v_add3_u32 v8, s56, v13, v176
	v_mul_f32_e32 v23, 0x3fb8aa3b, v23
	v_cvt_pk_bf16_f32 v3, v54, v44
	ds_write_b128 v8, v[0:3]
	v_cvt_pk_bf16_f32 v0, v7, v10
	v_cvt_pk_bf16_f32 v1, v26, v15
	v_cvt_pk_bf16_f32 v2, v24, v53
	v_add3_u32 v7, s57, v13, v176
	v_exp_f32_e32 v23, v23
	v_cvt_pk_bf16_f32 v3, v22, v45
	ds_write_b128 v7, v[0:3]
	v_cvt_pk_bf16_f32 v0, v6, v9
	v_cvt_pk_bf16_f32 v1, v14, v20
	v_cvt_pk_bf16_f32 v2, v4, v5
	v_lshl_add_u64 v[4:5], v[118:119], 0, s[8:9]
	v_mov_b32_e32 v17, v177
	v_lshl_add_u64 v[8:9], v[4:5], 0, v[16:17]
	v_add_co_u32_e32 v4, vcc, s34, v8
	v_mul_f32_e32 v23, v23, v28
	s_nop 0
	v_addc_co_u32_e32 v5, vcc, 0, v9, vcc
	v_cvt_pk_bf16_f32 v3, v39, v23
	global_load_dwordx4 v[4:7], v[4:5], off offset:2048
	v_lshl_add_u64 v[8:9], v[8:9], 0, s[2:3]
	global_load_dwordx4 v[8:11], v[8:9], off offset:16
	v_add3_u32 v12, s58, v13, v176
	ds_write_b128 v12, v[0:3]
	v_lshlrev_b32_e32 v16, 1, v170
	v_mul_u32_u24_e32 v17, 0x900, v19
	v_add3_u32 v16, s59, v16, v17
	s_cselect_b64 s[2:3], -1, 0
	s_addk_i32 s0, 0xf000
	s_lshr_b32 s0, s0, 11
	s_ashr_i32 s1, s12, 5
	s_cmp_gt_i32 s61, 63
	s_cselect_b64 s[18:19], -1, 0
	s_and_b64 vcc, s[18:19], exec
	s_cselect_b32 s13, s0, s1
	s_lshl_b32 s7, s13, 2
	s_or_b32 s16, s7, 2
	s_lshl_b64 s[0:1], s[16:17], 18
	s_add_u32 s0, s25, s0
	s_addc_u32 s1, s26, s1
	s_or_b32 s14, s7, 3
	s_waitcnt vmcnt(1)
	v_lshlrev_b32_e32 v0, 16, v4
	v_cvt_pk_bf16_f32 v0, v0, v177
	v_and_b32_e32 v1, 0xffff0000, v4
	ds_write_b16 v16, v0
	v_cvt_pk_bf16_f32 v0, v1, v177
	v_lshlrev_b32_e32 v2, 16, v5
	ds_write_b16 v16, v0 offset:144
	v_cvt_pk_bf16_f32 v0, v2, v177
	v_and_b32_e32 v3, 0xffff0000, v5
	ds_write_b16 v16, v0 offset:288
	v_cvt_pk_bf16_f32 v0, v3, v177
	v_lshlrev_b32_e32 v4, 16, v6
	ds_write_b16 v16, v0 offset:432
	v_cvt_pk_bf16_f32 v0, v4, v177
	v_and_b32_e32 v5, 0xffff0000, v6
	ds_write_b16 v16, v0 offset:576
	v_cvt_pk_bf16_f32 v0, v5, v177
	v_lshlrev_b32_e32 v6, 16, v7
	ds_write_b16 v16, v0 offset:720
	v_cvt_pk_bf16_f32 v0, v6, v177
	v_and_b32_e32 v7, 0xffff0000, v7
	ds_write_b16 v16, v0 offset:864
	v_cvt_pk_bf16_f32 v0, v7, v177
	s_waitcnt vmcnt(0)
	v_lshlrev_b32_e32 v12, 16, v8
	ds_write_b16 v16, v0 offset:1008
	v_cvt_pk_bf16_f32 v0, v12, v177
	v_and_b32_e32 v8, 0xffff0000, v8
	ds_write_b16 v16, v0 offset:1152
	v_cvt_pk_bf16_f32 v0, v8, v177
	v_lshlrev_b32_e32 v13, 16, v9
	ds_write_b16 v16, v0 offset:1296
	v_cvt_pk_bf16_f32 v0, v13, v177
	v_and_b32_e32 v9, 0xffff0000, v9
	ds_write_b16 v16, v0 offset:1440
	v_cvt_pk_bf16_f32 v0, v9, v177
	v_lshlrev_b32_e32 v14, 16, v10
	ds_write_b16 v16, v0 offset:1584
	v_cvt_pk_bf16_f32 v0, v14, v177
	v_and_b32_e32 v10, 0xffff0000, v10
	ds_write_b16 v16, v0 offset:1728
	v_cvt_pk_bf16_f32 v0, v10, v177
	v_lshlrev_b32_e32 v15, 16, v11
	ds_write_b16 v16, v0 offset:1872
	v_cvt_pk_bf16_f32 v0, v15, v177
	v_and_b32_e32 v11, 0xffff0000, v11
	ds_write_b16 v16, v0 offset:2016
	v_cvt_pk_bf16_f32 v0, v11, v177
	ds_write_b16 v16, v0 offset:2160
	v_lshlrev_b32_e32 v0, 11, v171
	v_and_b32_e32 v2, 0x7800, v0
	v_mov_b32_e32 v3, v177
	v_lshl_add_u64 v[0:1], s[0:1], 0, v[2:3]
	s_lshl_b64 s[0:1], s[14:15], 18
	s_add_u32 s0, s25, s0
	s_addc_u32 s1, s26, s1
	v_lshl_add_u64 v[2:3], s[0:1], 0, v[2:3]
	s_cbranch_vccz .LBB0_1370
	v_readlane_b32 s68, v254, 16
	v_readlane_b32 s69, v254, 17
	s_sub_i32 s70, s61, 64
	s_lshl_b32 s70, s70, 3
	s_or_b32 s70, s70, s24
	s_mov_b32 s71, 0
	s_lshl_b64 s[70:71], s[70:71], 16
	s_add_u32 s68, s68, s70
	s_addc_u32 s69, s69, s71
	s_add_u32 s70, s68, 0x8000
	s_addc_u32 s71, s69, 0
	v_lshlrev_b32_e32 v186, 4, v171
	global_load_dwordx4 v[132:135], v186, s[68:69]
	global_load_dwordx4 v[128:131], v186, s[70:71]
	v_add_u32_e32 v187, 0x2000, v186
	global_load_dwordx4 v[140:143], v187, s[68:69]
	global_load_dwordx4 v[136:139], v187, s[70:71]
	v_add_u32_e32 v187, 0x4000, v186
	global_load_dwordx4 v[148:151], v187, s[68:69]
	global_load_dwordx4 v[144:147], v187, s[70:71]
	v_add_u32_e32 v187, 0x6000, v186
	global_load_dwordx4 v[156:159], v187, s[68:69]
	global_load_dwordx4 v[152:155], v187, s[70:71]
	v_ashrrev_i32_e32 v117, 31, v116
	s_branch .LBB0_1354
	v_ashrrev_i32_e32 v4, 4, v171
	v_ashrrev_i32_e32 v5, 31, v4
	v_lshlrev_b64 v[4:5], 2, v[4:5]
	v_lshl_add_u64 v[6:7], v[0:1], 0, v[4:5]
	v_lshl_add_u64 v[4:5], v[2:3], 0, v[4:5]
	global_load_dword v132, v[6:7], off
	global_load_dword v133, v[6:7], off offset:512
	global_load_dword v134, v[6:7], off offset:1024
	global_load_dword v135, v[6:7], off offset:1536
	global_load_dword v128, v[4:5], off
	global_load_dword v129, v[4:5], off offset:512
	global_load_dword v130, v[4:5], off offset:1024
	global_load_dword v131, v[4:5], off offset:1536
	v_cndmask_b32_e64 v4, 0, 1, s[18:19]
	v_cmp_ne_u32_e64 s[0:1], 1, v4
	s_andn2_b64 vcc, exec, s[18:19]
	s_cbranch_vccz .LBB0_1371
